# non-temporal (nt) stores in the four LayerNorm phases, on top of aligned GEMM K-loops + MMA-path cleanup
# speedup vs baseline: 1.0056x; 1.0022x over previous
.LBB0_838:
	v_cmp_lt_i32_e32 vcc, v106, v105
	v_lshl_add_u64 v[4:5], s[14:15], 0, v[34:35]
	v_lshl_add_u64 v[2:3], s[30:31], 0, v[36:37]
	v_cndmask_b32_e32 v6, v104, v106, vcc
	v_cmp_lt_i32_e32 vcc, v107, v105
	v_lshl_add_u64 v[12:13], v[4:5], 0, s[36:37]
	global_load_dwordx4 v[72:75], v36, s[30:31]
	global_load_dwordx4 v[68:71], v36, s[30:31] offset:1024
	global_load_dwordx4 v[76:79], v36, s[30:31] offset:2048
	global_load_dwordx4 v[80:83], v36, s[30:31] offset:3072
	v_cndmask_b32_e32 v7, v104, v107, vcc
	v_cmp_lt_i32_e32 vcc, v108, v105
	v_lshlrev_b32_e32 v131, 2, v6
	global_load_dwordx2 v[42:43], v[12:13], off offset:512
	global_load_dwordx2 v[46:47], v[12:13], off offset:1024
	global_load_dwordx2 v[50:51], v[12:13], off offset:1536
	global_load_dwordx2 v[54:55], v[12:13], off offset:2048
	global_load_dwordx2 v[58:59], v[12:13], off offset:2560
	global_load_dwordx2 v[62:63], v[12:13], off offset:3072
	v_cndmask_b32_e32 v8, v104, v108, vcc
	v_cmp_lt_i32_e32 vcc, v109, v105
	v_lshlrev_b32_e32 v178, 2, v7
	v_lshlrev_b32_e32 v179, 2, v8
	v_cndmask_b32_e32 v9, v104, v109, vcc
	v_cmp_lt_i32_e32 vcc, v110, v105
	global_load_dwordx2 v[160:161], v[12:13], off offset:3584
	v_lshlrev_b32_e32 v180, 2, v9
	v_cndmask_b32_e32 v10, v104, v110, vcc
	v_cmp_lt_i32_e32 vcc, v111, v105
	v_add_co_u32_e64 v38, s[4:5], s3, v4
	s_nop 0
	v_cndmask_b32_e32 v11, v104, v111, vcc
	v_add_co_u32_e32 v14, vcc, 0xf8000000, v4
	v_addc_co_u32_e64 v39, s[4:5], 0, v5, s[4:5]
	s_nop 0
	v_addc_co_u32_e32 v15, vcc, -1, v5, vcc
	v_add_co_u32_e32 v6, vcc, s3, v2
	global_load_dwordx2 v[66:67], v[14:15], off
	s_nop 0
	v_addc_co_u32_e32 v7, vcc, 0, v3, vcc
	v_add_co_u32_e32 v8, vcc, s7, v2
	global_load_dwordx4 v[84:87], v[6:7], off offset:1024
	global_load_dwordx4 v[88:91], v[6:7], off offset:2048
	global_load_dwordx4 v[92:95], v[6:7], off offset:3072
	v_addc_co_u32_e32 v9, vcc, 0, v3, vcc
	v_add_co_u32_e32 v6, vcc, s9, v4
	global_load_dwordx4 v[96:99], v[8:9], off offset:-4096
	global_load_dwordx4 v[100:103], v[8:9], off
	v_addc_co_u32_e32 v7, vcc, -1, v5, vcc
	v_add_co_u32_e32 v4, vcc, s18, v4
	global_load_dwordx4 v[132:135], v[8:9], off offset:1024
	global_load_dwordx4 v[136:139], v[8:9], off offset:2048
	global_load_dwordx4 v[140:143], v[8:9], off offset:3072
	v_addc_co_u32_e32 v5, vcc, -1, v5, vcc
	global_load_dwordx2 v[162:163], v[6:7], off
	global_load_dwordx2 v[164:165], v[4:5], off offset:-3584
	global_load_dwordx2 v[166:167], v[4:5], off offset:-3072
	global_load_dwordx2 v[168:169], v[4:5], off offset:-2560
	v_add_co_u32_e32 v2, vcc, s19, v2
	v_lshlrev_b32_e32 v181, 2, v10
	s_nop 0
	v_addc_co_u32_e32 v3, vcc, 0, v3, vcc
	global_load_dwordx2 v[170:171], v[4:5], off offset:-2048
	global_load_dwordx2 v[172:173], v[4:5], off offset:-1536
	global_load_dwordx2 v[174:175], v[4:5], off offset:-1024
	global_load_dwordx2 v[176:177], v[4:5], off offset:-512
	global_load_dwordx4 v[144:147], v[2:3], off
	global_load_dwordx4 v[148:151], v[2:3], off offset:1024
	global_load_dwordx4 v[152:155], v[2:3], off offset:2048
	global_load_dwordx4 v[156:159], v[2:3], off offset:3072
	v_lshlrev_b32_e32 v182, 2, v11
	ds_read_b128 v[10:13], v1
	ds_read_b128 v[2:5], v1 offset:1024
	ds_read_b128 v[26:29], v1 offset:16384
	ds_read_b128 v[18:21], v1 offset:17408
	ds_read_b128 v[14:17], v1 offset:2048
	ds_read_b128 v[6:9], v1 offset:3072
	ds_read_b128 v[30:33], v1 offset:18432
	ds_read_b128 v[22:25], v1 offset:19456
	v_mov_b32_e32 v115, 0
	v_mov_b32_e32 v116, 0
	v_mov_b32_e32 v117, 0
	v_mov_b32_e32 v119, 0
	v_mov_b32_e32 v118, 0
	v_mov_b32_e32 v120, 0
	v_mov_b32_e32 v121, 0
	v_mov_b32_e32 v123, 0
	v_mov_b32_e32 v122, 0
	v_mov_b32_e32 v124, 0
	v_mov_b32_e32 v125, 0
	v_mov_b32_e32 v127, 0
	v_mov_b32_e32 v126, 0
	v_mov_b32_e32 v128, 0
	v_mov_b32_e32 v129, 0
	v_mov_b32_e32 v130, 0
	s_add_i32 s6, s6, s8
	s_waitcnt vmcnt(27)
	v_lshlrev_b32_e32 v40, 16, v42
	v_and_b32_e32 v41, 0xffff0000, v42
	v_lshlrev_b32_e32 v42, 16, v43
	v_and_b32_e32 v43, 0xffff0000, v43
	s_waitcnt vmcnt(26)
	v_lshlrev_b32_e32 v44, 16, v46
	v_and_b32_e32 v45, 0xffff0000, v46
	v_lshlrev_b32_e32 v46, 16, v47
	v_and_b32_e32 v47, 0xffff0000, v47
	s_waitcnt vmcnt(25)
	v_lshlrev_b32_e32 v48, 16, v50
	v_and_b32_e32 v49, 0xffff0000, v50
	v_lshlrev_b32_e32 v50, 16, v51
	v_and_b32_e32 v51, 0xffff0000, v51
	s_waitcnt vmcnt(23)
	v_lshlrev_b32_e32 v56, 16, v58
	v_and_b32_e32 v57, 0xffff0000, v58
	v_lshlrev_b32_e32 v58, 16, v59
	v_and_b32_e32 v59, 0xffff0000, v59
	v_fmac_f32_e32 v40, 0x3fb504f3, v68
	v_fmac_f32_e32 v41, 0x3fb504f3, v69
	v_fmac_f32_e32 v42, 0x3fb504f3, v70
	v_fmac_f32_e32 v43, 0x3fb504f3, v71
	v_fmac_f32_e32 v46, 0x3fb504f3, v78
	v_fmac_f32_e32 v47, 0x3fb504f3, v79
	v_fmac_f32_e32 v48, 0x3fb504f3, v80
	v_fmac_f32_e32 v49, 0x3fb504f3, v81
	v_fmac_f32_e32 v50, 0x3fb504f3, v82
	v_fmac_f32_e32 v51, 0x3fb504f3, v83
	s_waitcnt vmcnt(21)
	v_lshlrev_b32_e32 v68, 16, v160
	s_waitcnt vmcnt(20)
	v_lshlrev_b32_e32 v64, 16, v66
	v_and_b32_e32 v65, 0xffff0000, v66
	v_lshlrev_b32_e32 v66, 16, v67
	v_and_b32_e32 v67, 0xffff0000, v67
	v_fmac_f32_e32 v64, 0x3fb504f3, v72
	v_fmac_f32_e32 v65, 0x3fb504f3, v73
	v_fmac_f32_e32 v66, 0x3fb504f3, v74
	v_fmac_f32_e32 v67, 0x3fb504f3, v75
	v_and_b32_e32 v69, 0xffff0000, v160
	v_lshlrev_b32_e32 v70, 16, v161
	v_and_b32_e32 v71, 0xffff0000, v161
	v_add_f32_e32 v72, v40, v41
	v_add_f32_e32 v73, v42, v43
	s_waitcnt vmcnt(19)
	v_fmac_f32_e32 v56, 0x3fb504f3, v84
	v_fmac_f32_e32 v57, 0x3fb504f3, v85
	v_fmac_f32_e32 v58, 0x3fb504f3, v86
	v_fmac_f32_e32 v59, 0x3fb504f3, v87
	v_add_f32_e32 v78, v64, v65
	v_add_f32_e32 v79, v66, v67
	v_fmac_f32_e32 v44, 0x3fb504f3, v76
	v_fmac_f32_e32 v45, 0x3fb504f3, v77
	v_add_f32_e32 v76, v48, v49
	v_add_f32_e32 v77, v50, v51
	s_waitcnt vmcnt(17)
	v_fmac_f32_e32 v68, 0x3fb504f3, v92
	v_fmac_f32_e32 v69, 0x3fb504f3, v93
	v_fmac_f32_e32 v70, 0x3fb504f3, v94
	v_fmac_f32_e32 v71, 0x3fb504f3, v95
	v_add_f32_e32 v160, v72, v73
	v_add_f32_e32 v72, v56, v57
	v_add_f32_e32 v73, v58, v59
	v_add_f32_e32 v78, v78, v79
	v_lshlrev_b32_e32 v52, 16, v54
	v_and_b32_e32 v53, 0xffff0000, v54
	v_lshlrev_b32_e32 v54, 16, v55
	v_and_b32_e32 v55, 0xffff0000, v55
	v_lshlrev_b32_e32 v60, 16, v62
	v_and_b32_e32 v61, 0xffff0000, v62
	v_lshlrev_b32_e32 v62, 16, v63
	v_and_b32_e32 v63, 0xffff0000, v63
	v_add_f32_e32 v74, v44, v45
	v_add_f32_e32 v75, v46, v47
	v_add_f32_e32 v183, v76, v77
	v_add_f32_e32 v76, v68, v69
	v_add_f32_e32 v77, v70, v71
	v_add_f32_e32 v184, v72, v73
	s_waitcnt vmcnt(11)
	v_lshlrev_b32_e32 v72, 16, v162
	v_and_b32_e32 v73, 0xffff0000, v162
	v_add_f32_e32 v162, 0, v78
	v_fmac_f32_e32 v60, 0x3fb504f3, v88
	v_fmac_f32_e32 v61, 0x3fb504f3, v89
	v_fmac_f32_e32 v62, 0x3fb504f3, v90
	v_fmac_f32_e32 v63, 0x3fb504f3, v91
	v_add_f32_e32 v161, v74, v75
	v_fmac_f32_e32 v52, 0x3fb504f3, v96
	v_fmac_f32_e32 v53, 0x3fb504f3, v97
	v_fmac_f32_e32 v54, 0x3fb504f3, v98
	v_fmac_f32_e32 v55, 0x3fb504f3, v99
	v_add_f32_e32 v186, v76, v77
	s_waitcnt vmcnt(10)
	v_lshlrev_b32_e32 v76, 16, v164
	v_add_f32_e32 v160, v162, v160
	v_add_f32_e32 v74, v60, v61
	v_add_f32_e32 v75, v62, v63
	v_add_f32_e32 v79, v52, v53
	v_add_f32_e32 v80, v54, v55
	v_fmac_f32_e32 v76, 0x3fb504f3, v132
	v_add_f32_e32 v132, v160, v161
	v_add_f32_e32 v185, v74, v75
	v_lshlrev_b32_e32 v74, 16, v163
	v_and_b32_e32 v75, 0xffff0000, v163
	v_add_f32_e32 v163, v79, v80
	v_add_f32_e32 v132, v132, v183
	v_add_f32_e32 v132, v132, v163
	v_fmac_f32_e32 v72, 0x3fb504f3, v100
	v_fmac_f32_e32 v73, 0x3fb504f3, v101
	v_fmac_f32_e32 v74, 0x3fb504f3, v102
	v_fmac_f32_e32 v75, 0x3fb504f3, v103
	v_and_b32_e32 v77, 0xffff0000, v164
	v_lshlrev_b32_e32 v78, 16, v165
	v_and_b32_e32 v79, 0xffff0000, v165
	v_add_f32_e32 v132, v132, v184
	s_waitcnt vmcnt(9)
	v_lshlrev_b32_e32 v80, 16, v166
	v_and_b32_e32 v81, 0xffff0000, v166
	v_lshlrev_b32_e32 v82, 16, v167
	v_and_b32_e32 v83, 0xffff0000, v167
	v_add_f32_e32 v162, v72, v73
	v_add_f32_e32 v164, v74, v75
	v_fmac_f32_e32 v77, 0x3fb504f3, v133
	v_fmac_f32_e32 v78, 0x3fb504f3, v134
	v_fmac_f32_e32 v79, 0x3fb504f3, v135
	v_add_f32_e32 v132, v132, v185
	s_waitcnt vmcnt(8)
	v_lshlrev_b32_e32 v84, 16, v168
	v_and_b32_e32 v85, 0xffff0000, v168
	v_lshlrev_b32_e32 v86, 16, v169
	v_and_b32_e32 v87, 0xffff0000, v169
	v_fmac_f32_e32 v80, 0x3fb504f3, v136
	v_fmac_f32_e32 v81, 0x3fb504f3, v137
	v_fmac_f32_e32 v82, 0x3fb504f3, v138
	v_fmac_f32_e32 v83, 0x3fb504f3, v139
	v_add_f32_e32 v133, v162, v164
	v_add_f32_e32 v134, v76, v77
	v_add_f32_e32 v135, v78, v79
	v_add_f32_e32 v132, v132, v186
	s_waitcnt vmcnt(7)
	v_lshlrev_b32_e32 v88, 16, v170
	v_and_b32_e32 v89, 0xffff0000, v170
	v_lshlrev_b32_e32 v90, 16, v171
	v_and_b32_e32 v91, 0xffff0000, v171
	v_fmac_f32_e32 v84, 0x3fb504f3, v140
	v_fmac_f32_e32 v85, 0x3fb504f3, v141
	v_fmac_f32_e32 v86, 0x3fb504f3, v142
	v_fmac_f32_e32 v87, 0x3fb504f3, v143
	v_add_f32_e32 v136, v80, v81
	v_add_f32_e32 v137, v82, v83
	v_add_f32_e32 v134, v134, v135
	v_add_f32_e32 v132, v132, v133
	s_waitcnt vmcnt(6)
	v_lshlrev_b32_e32 v92, 16, v172
	v_and_b32_e32 v93, 0xffff0000, v172
	v_lshlrev_b32_e32 v94, 16, v173
	v_and_b32_e32 v95, 0xffff0000, v173
	s_waitcnt vmcnt(3)
	v_fmac_f32_e32 v88, 0x3fb504f3, v144
	v_fmac_f32_e32 v89, 0x3fb504f3, v145
	v_fmac_f32_e32 v90, 0x3fb504f3, v146
	v_fmac_f32_e32 v91, 0x3fb504f3, v147
	v_add_f32_e32 v138, v84, v85
	v_add_f32_e32 v139, v86, v87
	v_add_f32_e32 v135, v136, v137
	v_add_f32_e32 v132, v132, v134
	v_lshlrev_b32_e32 v96, 16, v174
	v_and_b32_e32 v97, 0xffff0000, v174
	v_lshlrev_b32_e32 v98, 16, v175
	v_and_b32_e32 v99, 0xffff0000, v175
	s_waitcnt vmcnt(2)
	v_fmac_f32_e32 v92, 0x3fb504f3, v148
	v_fmac_f32_e32 v93, 0x3fb504f3, v149
	v_fmac_f32_e32 v94, 0x3fb504f3, v150
	v_fmac_f32_e32 v95, 0x3fb504f3, v151
	v_add_f32_e32 v140, v88, v89
	v_add_f32_e32 v141, v90, v91
	v_add_f32_e32 v136, v138, v139
	v_add_f32_e32 v132, v132, v135
	v_lshlrev_b32_e32 v100, 16, v176
	v_and_b32_e32 v101, 0xffff0000, v176
	v_lshlrev_b32_e32 v102, 16, v177
	v_and_b32_e32 v103, 0xffff0000, v177
	s_waitcnt vmcnt(1)
	v_fmac_f32_e32 v96, 0x3fb504f3, v152
	v_fmac_f32_e32 v97, 0x3fb504f3, v153
	v_fmac_f32_e32 v98, 0x3fb504f3, v154
	v_fmac_f32_e32 v99, 0x3fb504f3, v155
	v_add_f32_e32 v142, v92, v93
	v_add_f32_e32 v143, v94, v95
	v_add_f32_e32 v137, v140, v141
	v_add_f32_e32 v132, v132, v136
	s_waitcnt vmcnt(0)
	v_fmac_f32_e32 v100, 0x3fb504f3, v156
	v_fmac_f32_e32 v101, 0x3fb504f3, v157
	v_fmac_f32_e32 v102, 0x3fb504f3, v158
	v_fmac_f32_e32 v103, 0x3fb504f3, v159
	v_add_f32_e32 v144, v96, v97
	v_add_f32_e32 v145, v98, v99
	v_add_f32_e32 v138, v142, v143
	v_add_f32_e32 v132, v132, v137
	v_add_f32_e32 v146, v100, v101
	v_add_f32_e32 v147, v102, v103
	v_add_f32_e32 v139, v144, v145
	v_add_f32_e32 v132, v132, v138
	v_add_f32_e32 v140, v146, v147
	v_add_f32_e32 v132, v132, v139
	v_add_f32_e32 v132, v132, v140
	ds_bpermute_b32 v133, v131, v132
	s_waitcnt lgkmcnt(0)
	v_add_f32_e32 v132, v132, v133
	ds_bpermute_b32 v133, v178, v132
	s_waitcnt lgkmcnt(0)
	v_add_f32_e32 v132, v132, v133
	ds_bpermute_b32 v133, v179, v132
	s_waitcnt lgkmcnt(0)
	v_add_f32_e32 v132, v132, v133
	ds_bpermute_b32 v133, v180, v132
	s_waitcnt lgkmcnt(0)
	v_add_f32_e32 v132, v132, v133
	ds_bpermute_b32 v133, v181, v132
	s_waitcnt lgkmcnt(0)
	v_add_f32_e32 v132, v132, v133
	ds_bpermute_b32 v133, v182, v132
	s_waitcnt lgkmcnt(0)
	v_add_f32_e32 v132, v132, v133
	v_fmac_f32_e32 v65, 0xb9800000, v132
	v_fmac_f32_e32 v64, 0xb9800000, v132
	v_fmac_f32_e32 v67, 0xb9800000, v132
	v_fmac_f32_e32 v66, 0xb9800000, v132
	v_fmac_f32_e32 v41, 0xb9800000, v132
	v_fmac_f32_e32 v40, 0xb9800000, v132
	v_fmac_f32_e32 v43, 0xb9800000, v132
	v_fmac_f32_e32 v42, 0xb9800000, v132
	v_fmac_f32_e32 v45, 0xb9800000, v132
	v_fmac_f32_e32 v44, 0xb9800000, v132
	v_fmac_f32_e32 v47, 0xb9800000, v132
	v_fmac_f32_e32 v46, 0xb9800000, v132
	v_fmac_f32_e32 v51, 0xb9800000, v132
	v_fmac_f32_e32 v50, 0xb9800000, v132
	v_fmac_f32_e32 v49, 0xb9800000, v132
	v_fmac_f32_e32 v48, 0xb9800000, v132
	v_fmac_f32_e32 v53, 0xb9800000, v132
	v_fmac_f32_e32 v52, 0xb9800000, v132
	v_fmac_f32_e32 v55, 0xb9800000, v132
	v_fmac_f32_e32 v54, 0xb9800000, v132
	v_fmac_f32_e32 v57, 0xb9800000, v132
	v_fmac_f32_e32 v56, 0xb9800000, v132
	v_fmac_f32_e32 v59, 0xb9800000, v132
	v_fmac_f32_e32 v58, 0xb9800000, v132
	v_fmac_f32_e32 v63, 0xb9800000, v132
	v_fmac_f32_e32 v62, 0xb9800000, v132
	v_fmac_f32_e32 v61, 0xb9800000, v132
	v_fmac_f32_e32 v60, 0xb9800000, v132
	v_fmac_f32_e32 v69, 0xb9800000, v132
	v_fmac_f32_e32 v68, 0xb9800000, v132
	v_fmac_f32_e32 v71, 0xb9800000, v132
	v_fmac_f32_e32 v70, 0xb9800000, v132
	v_fmac_f32_e32 v73, 0xb9800000, v132
	v_fmac_f32_e32 v72, 0xb9800000, v132
	v_fmac_f32_e32 v75, 0xb9800000, v132
	v_fmac_f32_e32 v74, 0xb9800000, v132
	v_fmac_f32_e32 v79, 0xb9800000, v132
	v_fmac_f32_e32 v78, 0xb9800000, v132
	v_fmac_f32_e32 v77, 0xb9800000, v132
	v_fmac_f32_e32 v76, 0xb9800000, v132
	v_fmac_f32_e32 v81, 0xb9800000, v132
	v_fmac_f32_e32 v80, 0xb9800000, v132
	v_fmac_f32_e32 v83, 0xb9800000, v132
	v_fmac_f32_e32 v82, 0xb9800000, v132
	v_fmac_f32_e32 v85, 0xb9800000, v132
	v_fmac_f32_e32 v84, 0xb9800000, v132
	v_fmac_f32_e32 v87, 0xb9800000, v132
	v_fmac_f32_e32 v86, 0xb9800000, v132
	v_fmac_f32_e32 v91, 0xb9800000, v132
	v_fmac_f32_e32 v90, 0xb9800000, v132
	v_fmac_f32_e32 v89, 0xb9800000, v132
	v_fmac_f32_e32 v88, 0xb9800000, v132
	v_fmac_f32_e32 v93, 0xb9800000, v132
	v_fmac_f32_e32 v92, 0xb9800000, v132
	v_fmac_f32_e32 v95, 0xb9800000, v132
	v_fmac_f32_e32 v94, 0xb9800000, v132
	v_fmac_f32_e32 v97, 0xb9800000, v132
	v_fmac_f32_e32 v96, 0xb9800000, v132
	v_fmac_f32_e32 v99, 0xb9800000, v132
	v_fmac_f32_e32 v98, 0xb9800000, v132
	v_fmac_f32_e32 v103, 0xb9800000, v132
	v_fmac_f32_e32 v102, 0xb9800000, v132
	v_fmac_f32_e32 v101, 0xb9800000, v132
	v_fmac_f32_e32 v100, 0xb9800000, v132
	v_pk_mul_f32 v[132:133], v[66:67], v[66:67]
	v_pk_mul_f32 v[134:135], v[64:65], v[64:65]
	v_pk_mul_f32 v[136:137], v[42:43], v[42:43]
	v_pk_mul_f32 v[138:139], v[40:41], v[40:41]
	v_pk_mov_b32 v[176:177], v[134:135], v[132:133] op_sel:[1,0]
	v_mov_b32_e32 v135, v133
	v_pk_mov_b32 v[132:133], v[138:139], v[136:137] op_sel:[1,0]
	v_mov_b32_e32 v139, v137
	v_mul_f32_e32 v140, v44, v44
	v_mul_f32_e32 v142, v46, v46
	v_pk_add_f32 v[134:135], v[176:177], v[134:135]
	v_pk_add_f32 v[132:133], v[132:133], v[138:139]
	v_pk_fma_f32 v[136:137], v[44:45], v[44:45], v[140:141] op_sel_hi:[1,1,0]
	v_pk_fma_f32 v[140:141], v[46:47], v[46:47], v[142:143] op_sel_hi:[1,1,0]
	v_pk_add_f32 v[134:135], v[134:135], v[134:135] op_sel_hi:[0,1]
	v_pk_add_f32 v[132:133], v[132:133], v[132:133] op_sel_hi:[0,1]
	v_pk_mul_f32 v[144:145], v[54:55], v[54:55]
	v_pk_mul_f32 v[146:147], v[52:53], v[52:53]
	v_mul_f32_e32 v136, v48, v48
	v_mul_f32_e32 v140, v49, v49
	v_mul_f32_e32 v134, v50, v50
	v_mul_f32_e32 v132, v51, v51
	v_pk_mov_b32 v[142:143], v[146:147], v[144:145] op_sel:[1,0]
	v_mov_b32_e32 v147, v145
	v_pk_add_f32 v[136:137], v[136:137], v[140:141]
	v_pk_add_f32 v[132:133], v[134:135], v[132:133]
	v_mul_f32_e32 v148, v56, v56
	v_mul_f32_e32 v150, v58, v58
	v_pk_add_f32 v[138:139], v[142:143], v[146:147]
	v_pk_add_f32 v[132:133], v[136:137], v[132:133]
	v_pk_fma_f32 v[144:145], v[56:57], v[56:57], v[148:149] op_sel_hi:[1,1,0]
	v_pk_fma_f32 v[148:149], v[58:59], v[58:59], v[150:151] op_sel_hi:[1,1,0]
	v_pk_add_f32 v[138:139], v[138:139], v[138:139] op_sel_hi:[0,1]
	v_pk_add_f32 v[132:133], v[132:133], v[132:133] op_sel_hi:[0,1]
	v_pk_mul_f32 v[152:153], v[70:71], v[70:71]
	v_pk_mul_f32 v[154:155], v[68:69], v[68:69]
	v_mul_f32_e32 v144, v60, v60
	v_mul_f32_e32 v148, v61, v61
	v_mul_f32_e32 v138, v62, v62
	v_mul_f32_e32 v132, v63, v63
	v_pk_mov_b32 v[150:151], v[154:155], v[152:153] op_sel:[1,0]
	v_mov_b32_e32 v155, v153
	v_pk_add_f32 v[140:141], v[144:145], v[148:149]
	v_pk_add_f32 v[132:133], v[138:139], v[132:133]
	v_mul_f32_e32 v156, v72, v72
	v_mul_f32_e32 v158, v74, v74
	v_pk_add_f32 v[142:143], v[150:151], v[154:155]
	v_pk_add_f32 v[132:133], v[140:141], v[132:133]
	v_pk_fma_f32 v[152:153], v[72:73], v[72:73], v[156:157] op_sel_hi:[1,1,0]
	v_pk_fma_f32 v[156:157], v[74:75], v[74:75], v[158:159] op_sel_hi:[1,1,0]
	v_pk_add_f32 v[142:143], v[142:143], v[142:143] op_sel_hi:[0,1]
	v_pk_add_f32 v[132:133], v[132:133], v[132:133] op_sel_hi:[0,1]
	v_pk_mul_f32 v[160:161], v[82:83], v[82:83]
	v_pk_mul_f32 v[162:163], v[80:81], v[80:81]
	v_mul_f32_e32 v152, v76, v76
	v_mul_f32_e32 v156, v77, v77
	v_mul_f32_e32 v142, v78, v78
	v_mul_f32_e32 v132, v79, v79
	v_pk_mov_b32 v[158:159], v[162:163], v[160:161] op_sel:[1,0]
	v_mov_b32_e32 v163, v161
	v_pk_add_f32 v[144:145], v[152:153], v[156:157]
	v_pk_add_f32 v[132:133], v[142:143], v[132:133]
	v_mul_f32_e32 v164, v84, v84
	v_mul_f32_e32 v166, v86, v86
	v_pk_add_f32 v[146:147], v[158:159], v[162:163]
	v_pk_add_f32 v[132:133], v[144:145], v[132:133]
	v_pk_fma_f32 v[160:161], v[84:85], v[84:85], v[164:165] op_sel_hi:[1,1,0]
	v_pk_fma_f32 v[164:165], v[86:87], v[86:87], v[166:167] op_sel_hi:[1,1,0]
	v_pk_add_f32 v[146:147], v[146:147], v[146:147] op_sel_hi:[0,1]
	v_pk_add_f32 v[132:133], v[132:133], v[132:133] op_sel_hi:[0,1]
	v_pk_mul_f32 v[168:169], v[94:95], v[94:95]
	v_pk_mul_f32 v[170:171], v[92:93], v[92:93]
	v_mul_f32_e32 v160, v88, v88
	v_mul_f32_e32 v164, v89, v89
	v_mul_f32_e32 v146, v90, v90
	v_mul_f32_e32 v132, v91, v91
	v_pk_mov_b32 v[166:167], v[170:171], v[168:169] op_sel:[1,0]
	v_mov_b32_e32 v171, v169
	v_pk_add_f32 v[148:149], v[160:161], v[164:165]
	v_pk_add_f32 v[132:133], v[146:147], v[132:133]
	v_mul_f32_e32 v172, v96, v96
	v_mul_f32_e32 v174, v98, v98
	v_pk_add_f32 v[150:151], v[166:167], v[170:171]
	v_pk_add_f32 v[132:133], v[148:149], v[132:133]
	v_pk_fma_f32 v[168:169], v[96:97], v[96:97], v[172:173] op_sel_hi:[1,1,0]
	v_pk_fma_f32 v[172:173], v[98:99], v[98:99], v[174:175] op_sel_hi:[1,1,0]
	v_pk_add_f32 v[150:151], v[150:151], v[150:151] op_sel_hi:[0,1]
	v_pk_add_f32 v[132:133], v[132:133], v[132:133] op_sel_hi:[0,1]
	v_mul_f32_e32 v168, v100, v100
	v_mul_f32_e32 v172, v101, v101
	v_mul_f32_e32 v150, v102, v102
	v_mul_f32_e32 v132, v103, v103
	v_pk_add_f32 v[152:153], v[168:169], v[172:173]
	v_pk_add_f32 v[132:133], v[150:151], v[132:133]
	s_nop 0
	v_pk_add_f32 v[132:133], v[152:153], v[132:133]
	s_nop 0
	v_add_f32_e32 v132, v132, v133
	ds_bpermute_b32 v131, v131, v132
	s_waitcnt lgkmcnt(0)
	v_add_f32_e32 v131, v132, v131
	ds_bpermute_b32 v132, v178, v131
	s_waitcnt lgkmcnt(0)
	v_add_f32_e32 v131, v131, v132
	ds_bpermute_b32 v132, v179, v131
	s_waitcnt lgkmcnt(0)
	v_add_f32_e32 v131, v131, v132
	ds_bpermute_b32 v132, v180, v131
	s_waitcnt lgkmcnt(0)
	v_add_f32_e32 v131, v131, v132
	ds_bpermute_b32 v132, v181, v131
	s_waitcnt lgkmcnt(0)
	v_add_f32_e32 v131, v131, v132
	ds_bpermute_b32 v132, v182, v131
	s_waitcnt lgkmcnt(0)
	v_add_f32_e32 v131, v131, v132
	v_fmamk_f32 v131, v131, 0x39800000, v112
	v_mul_f32_e32 v132, 0x4f800000, v131
	v_cmp_gt_f32_e32 vcc, s24, v131
	s_nop 1
	v_cndmask_b32_e32 v131, v131, v132, vcc
	v_sqrt_f32_e32 v132, v131
	s_nop 0
	v_add_u32_e32 v133, -1, v132
	v_add_u32_e32 v134, 1, v132
	v_fma_f32 v135, -v133, v132, v131
	v_fma_f32 v136, -v134, v132, v131
	v_cmp_ge_f32_e64 s[4:5], 0, v135
	s_nop 1
	v_cndmask_b32_e64 v132, v132, v133, s[4:5]
	v_cmp_lt_f32_e64 s[4:5], 0, v136
	s_nop 1
	v_cndmask_b32_e64 v132, v132, v134, s[4:5]
	v_mul_f32_e32 v133, 0x37800000, v132
	v_cndmask_b32_e32 v132, v132, v133, vcc
	v_cmp_class_f32_e32 vcc, v131, v113
	s_nop 1
	v_cndmask_b32_e32 v131, v132, v131, vcc
	v_div_scale_f32 v132, s[4:5], v131, v131, 1.0
	v_rcp_f32_e32 v134, v132
	v_div_scale_f32 v133, vcc, 1.0, v131, 1.0
	v_fma_f32 v135, -v132, v134, 1.0
	v_fmac_f32_e32 v134, v135, v134
	v_mul_f32_e32 v135, v133, v134
	v_fma_f32 v136, -v132, v135, v133
	v_fmac_f32_e32 v135, v136, v134
	v_fma_f32 v132, -v132, v135, v133
	v_div_fmas_f32 v132, v132, v134, v135
	v_div_fixup_f32 v132, v132, v131, 1.0
	v_pk_mul_f32 v[64:65], v[64:65], v[132:133] op_sel_hi:[1,0]
	v_pk_mul_f32 v[40:41], v[40:41], v[132:133] op_sel_hi:[1,0]
	v_pk_fma_f32 v[10:11], v[10:11], v[64:65], v[26:27]
	v_pk_fma_f32 v[2:3], v[2:3], v[40:41], v[18:19]
	v_cvt_pk_fp8_f32 v115, v10, v11
	v_pk_mul_f32 v[66:67], v[66:67], v[132:133] op_sel_hi:[1,0]
	v_pk_mul_f32 v[44:45], v[44:45], v[132:133] op_sel_hi:[1,0]
	v_pk_mul_f32 v[48:49], v[48:49], v[132:133] op_sel_hi:[1,0]
	v_cvt_pk_fp8_f32 v116, v2, v3
	v_pk_fma_f32 v[12:13], v[12:13], v[66:67], v[28:29]
	v_pk_fma_f32 v[14:15], v[14:15], v[44:45], v[30:31]
	v_pk_fma_f32 v[6:7], v[6:7], v[48:49], v[22:23]
	v_pk_mul_f32 v[42:43], v[42:43], v[132:133] op_sel_hi:[1,0]
	v_cvt_pk_fp8_f32 v117, v14, v15
	v_cvt_pk_fp8_f32 v119, v6, v7
	v_cvt_pk_fp8_f32 v115, v12, v13 op_sel:[0,0,1]
	v_pk_fma_f32 v[4:5], v[4:5], v[42:43], v[20:21]
	v_pk_mul_f32 v[46:47], v[46:47], v[132:133] op_sel_hi:[1,0]
	v_pk_mul_f32 v[50:51], v[50:51], v[132:133] op_sel_hi:[1,0]
	v_cvt_pk_fp8_f32 v116, v4, v5 op_sel:[0,0,1]
	v_pk_fma_f32 v[16:17], v[16:17], v[46:47], v[32:33]
	v_pk_fma_f32 v[8:9], v[8:9], v[50:51], v[24:25]
	v_cvt_pk_f16_f32 v19, v12, v13
	v_cvt_pk_f16_f32 v18, v10, v11
	v_cvt_pk_f16_f32 v11, v4, v5
	v_cvt_pk_f16_f32 v10, v2, v3
	v_cvt_pk_f16_f32 v3, v16, v17
	v_cvt_pk_f16_f32 v2, v14, v15
	v_cvt_pk_f16_f32 v15, v8, v9
	v_cvt_pk_f16_f32 v14, v6, v7
	global_store_dwordx2 v34, v[18:19], s[14:15] nt
	v_cvt_pk_fp8_f32 v117, v16, v17 op_sel:[0,0,1]
	v_cvt_pk_fp8_f32 v119, v8, v9 op_sel:[0,0,1]
	global_store_dword v114, v115, s[10:11] nt
	global_store_dwordx2 v34, v[10:11], s[14:15] offset:512 nt
	global_store_dword v114, v116, s[10:11] offset:256 nt
	global_store_dwordx2 v34, v[2:3], s[14:15] offset:1024 nt
	global_store_dword v114, v117, s[10:11] offset:512 nt
	global_store_dwordx2 v34, v[14:15], s[14:15] offset:1536 nt
	global_store_dword v114, v119, s[10:11] offset:768 nt
	v_pk_mul_f32 v[52:53], v[52:53], v[132:133] op_sel_hi:[1,0]
	ds_read_b128 v[2:5], v1 offset:4096
	ds_read_b128 v[6:9], v1 offset:5120
	ds_read_b128 v[10:13], v1 offset:20480
	ds_read_b128 v[14:17], v1 offset:21504
	ds_read_b128 v[18:21], v1 offset:6144
	ds_read_b128 v[22:25], v1 offset:7168
	ds_read_b128 v[26:29], v1 offset:22528
	ds_read_b128 v[30:33], v1 offset:23552
	s_waitcnt lgkmcnt(5)
	v_pk_fma_f32 v[2:3], v[2:3], v[52:53], v[10:11]
	v_pk_mul_f32 v[56:57], v[56:57], v[132:133] op_sel_hi:[1,0]
	v_cvt_pk_fp8_f32 v118, v2, v3
	s_waitcnt lgkmcnt(4)
	v_pk_fma_f32 v[6:7], v[6:7], v[56:57], v[14:15]
	v_pk_mul_f32 v[54:55], v[54:55], v[132:133] op_sel_hi:[1,0]
	v_pk_mul_f32 v[58:59], v[58:59], v[132:133] op_sel_hi:[1,0]
	v_pk_mul_f32 v[60:61], v[60:61], v[132:133] op_sel_hi:[1,0]
	v_pk_mul_f32 v[68:69], v[68:69], v[132:133] op_sel_hi:[1,0]
	v_cvt_pk_fp8_f32 v120, v6, v7
	v_pk_fma_f32 v[4:5], v[4:5], v[54:55], v[12:13]
	v_pk_fma_f32 v[8:9], v[8:9], v[58:59], v[16:17]
	s_waitcnt lgkmcnt(1)
	v_pk_fma_f32 v[12:13], v[60:61], v[18:19], v[26:27]
	s_waitcnt lgkmcnt(0)
	v_pk_fma_f32 v[16:17], v[68:69], v[22:23], v[30:31]
	v_cvt_pk_fp8_f32 v121, v12, v13
	v_cvt_pk_fp8_f32 v123, v16, v17
	v_cvt_pk_fp8_f32 v118, v4, v5 op_sel:[0,0,1]
	v_pk_mul_f32 v[62:63], v[62:63], v[132:133] op_sel_hi:[1,0]
	v_pk_mul_f32 v[70:71], v[70:71], v[132:133] op_sel_hi:[1,0]
	v_cvt_pk_fp8_f32 v120, v8, v9 op_sel:[0,0,1]
	v_pk_fma_f32 v[10:11], v[62:63], v[20:21], v[28:29]
	v_pk_fma_f32 v[14:15], v[70:71], v[24:25], v[32:33]
	v_cvt_pk_f16_f32 v18, v2, v3
	v_cvt_pk_f16_f32 v19, v4, v5
	v_cvt_pk_f16_f32 v2, v6, v7
	v_cvt_pk_f16_f32 v3, v8, v9
	v_cvt_pk_f16_f32 v6, v12, v13
	v_cvt_pk_f16_f32 v7, v10, v11
	v_cvt_pk_f16_f32 v12, v16, v17
	v_cvt_pk_f16_f32 v13, v14, v15
	global_store_dwordx2 v34, v[18:19], s[14:15] offset:2048 nt
	v_cvt_pk_fp8_f32 v121, v10, v11 op_sel:[0,0,1]
	v_cvt_pk_fp8_f32 v123, v14, v15 op_sel:[0,0,1]
	global_store_dword v114, v118, s[10:11] offset:1024 nt
	global_store_dwordx2 v34, v[2:3], s[14:15] offset:2560 nt
	global_store_dword v114, v120, s[10:11] offset:1280 nt
	global_store_dwordx2 v34, v[6:7], s[14:15] offset:3072 nt
	global_store_dword v114, v121, s[10:11] offset:1536 nt
	global_store_dwordx2 v34, v[12:13], s[14:15] offset:3584 nt
	global_store_dword v114, v123, s[10:11] offset:1792 nt
	v_pk_mul_f32 v[72:73], v[72:73], v[132:133] op_sel_hi:[1,0]
	ds_read_b128 v[2:5], v1 offset:8192
	ds_read_b128 v[6:9], v1 offset:9216
	ds_read_b128 v[10:13], v1 offset:24576
	ds_read_b128 v[14:17], v1 offset:25600
	ds_read_b128 v[18:21], v1 offset:10240
	ds_read_b128 v[22:25], v1 offset:11264
	ds_read_b128 v[26:29], v1 offset:26624
	ds_read_b128 v[30:33], v1 offset:27648
	s_waitcnt lgkmcnt(5)
	v_pk_fma_f32 v[2:3], v[72:73], v[2:3], v[10:11]
	v_pk_mul_f32 v[76:77], v[76:77], v[132:133] op_sel_hi:[1,0]
	v_cvt_pk_fp8_f32 v122, v2, v3
	s_waitcnt lgkmcnt(4)
	v_pk_fma_f32 v[6:7], v[76:77], v[6:7], v[14:15]
	v_pk_mul_f32 v[74:75], v[74:75], v[132:133] op_sel_hi:[1,0]
	v_pk_mul_f32 v[78:79], v[78:79], v[132:133] op_sel_hi:[1,0]
	v_pk_mul_f32 v[80:81], v[80:81], v[132:133] op_sel_hi:[1,0]
	v_pk_mul_f32 v[84:85], v[84:85], v[132:133] op_sel_hi:[1,0]
	v_cvt_pk_fp8_f32 v124, v6, v7
	v_pk_fma_f32 v[4:5], v[74:75], v[4:5], v[12:13]
	v_pk_fma_f32 v[8:9], v[78:79], v[8:9], v[16:17]
	s_waitcnt lgkmcnt(1)
	v_pk_fma_f32 v[12:13], v[80:81], v[18:19], v[26:27]
	s_waitcnt lgkmcnt(0)
	v_pk_fma_f32 v[16:17], v[84:85], v[22:23], v[30:31]
	v_cvt_pk_fp8_f32 v125, v12, v13
	v_cvt_pk_fp8_f32 v127, v16, v17
	v_cvt_pk_fp8_f32 v122, v4, v5 op_sel:[0,0,1]
	v_pk_mul_f32 v[82:83], v[82:83], v[132:133] op_sel_hi:[1,0]
	v_pk_mul_f32 v[86:87], v[86:87], v[132:133] op_sel_hi:[1,0]
	v_cvt_pk_fp8_f32 v124, v8, v9 op_sel:[0,0,1]
	v_pk_fma_f32 v[10:11], v[82:83], v[20:21], v[28:29]
	v_pk_fma_f32 v[14:15], v[86:87], v[24:25], v[32:33]
	v_cvt_pk_f16_f32 v18, v2, v3
	v_cvt_pk_f16_f32 v19, v4, v5
	v_cvt_pk_f16_f32 v2, v6, v7
	v_cvt_pk_f16_f32 v3, v8, v9
	v_cvt_pk_f16_f32 v6, v12, v13
	v_cvt_pk_f16_f32 v7, v10, v11
	v_cvt_pk_f16_f32 v12, v16, v17
	v_cvt_pk_f16_f32 v13, v14, v15
	global_store_dwordx2 v[38:39], v[18:19], off nt
	v_cvt_pk_fp8_f32 v125, v10, v11 op_sel:[0,0,1]
	v_cvt_pk_fp8_f32 v127, v14, v15 op_sel:[0,0,1]
	global_store_dword v114, v122, s[10:11] offset:2048 nt
	global_store_dwordx2 v[38:39], v[2:3], off offset:512 nt
	global_store_dword v114, v124, s[10:11] offset:2304 nt
	global_store_dwordx2 v[38:39], v[6:7], off offset:1024 nt
	global_store_dword v114, v125, s[10:11] offset:2560 nt
	global_store_dwordx2 v[38:39], v[12:13], off offset:1536 nt
	global_store_dword v114, v127, s[10:11] offset:2816 nt
	v_pk_mul_f32 v[88:89], v[88:89], v[132:133] op_sel_hi:[1,0]
	ds_read_b128 v[2:5], v1 offset:12288
	ds_read_b128 v[6:9], v1 offset:13312
	ds_read_b128 v[10:13], v1 offset:28672
	ds_read_b128 v[14:17], v1 offset:29696
	ds_read_b128 v[18:21], v1 offset:14336
	ds_read_b128 v[22:25], v1 offset:15360
	ds_read_b128 v[26:29], v1 offset:30720
	ds_read_b128 v[30:33], v1 offset:31744
	s_waitcnt lgkmcnt(5)
	v_pk_fma_f32 v[2:3], v[88:89], v[2:3], v[10:11]
	v_pk_mul_f32 v[92:93], v[92:93], v[132:133] op_sel_hi:[1,0]
	v_cvt_pk_fp8_f32 v126, v2, v3
	s_waitcnt lgkmcnt(4)
	v_pk_fma_f32 v[6:7], v[92:93], v[6:7], v[14:15]
	v_pk_mul_f32 v[90:91], v[90:91], v[132:133] op_sel_hi:[1,0]
	v_pk_mul_f32 v[94:95], v[94:95], v[132:133] op_sel_hi:[1,0]
	v_pk_mul_f32 v[96:97], v[96:97], v[132:133] op_sel_hi:[1,0]
	v_pk_mul_f32 v[100:101], v[100:101], v[132:133] op_sel_hi:[1,0]
	v_cvt_pk_fp8_f32 v128, v6, v7
	v_pk_fma_f32 v[4:5], v[90:91], v[4:5], v[12:13]
	v_pk_fma_f32 v[8:9], v[94:95], v[8:9], v[16:17]
	s_waitcnt lgkmcnt(1)
	v_pk_fma_f32 v[12:13], v[96:97], v[18:19], v[26:27]
	s_waitcnt lgkmcnt(0)
	v_pk_fma_f32 v[16:17], v[100:101], v[22:23], v[30:31]
	v_cvt_pk_fp8_f32 v129, v12, v13
	v_cvt_pk_fp8_f32 v130, v16, v17
	v_cvt_pk_fp8_f32 v126, v4, v5 op_sel:[0,0,1]
	v_pk_mul_f32 v[98:99], v[98:99], v[132:133] op_sel_hi:[1,0]
	v_pk_mul_f32 v[102:103], v[102:103], v[132:133] op_sel_hi:[1,0]
	v_cvt_pk_fp8_f32 v128, v8, v9 op_sel:[0,0,1]
	v_pk_fma_f32 v[10:11], v[98:99], v[20:21], v[28:29]
	v_pk_fma_f32 v[14:15], v[102:103], v[24:25], v[32:33]
	v_cvt_pk_f16_f32 v18, v2, v3
	v_cvt_pk_f16_f32 v19, v4, v5
	v_cvt_pk_f16_f32 v2, v6, v7
	v_cvt_pk_f16_f32 v3, v8, v9
	v_cvt_pk_f16_f32 v6, v12, v13
	v_cvt_pk_f16_f32 v7, v10, v11
	v_cvt_pk_f16_f32 v12, v16, v17
	v_cvt_pk_f16_f32 v13, v14, v15
	global_store_dwordx2 v[38:39], v[18:19], off offset:2048 nt
	v_cvt_pk_fp8_f32 v129, v10, v11 op_sel:[0,0,1]
	v_cvt_pk_fp8_f32 v130, v14, v15 op_sel:[0,0,1]
	global_store_dword v114, v126, s[10:11] offset:3072 nt
	global_store_dwordx2 v[38:39], v[2:3], off offset:2560 nt
	global_store_dword v114, v128, s[10:11] offset:3328 nt
	global_store_dwordx2 v[38:39], v[6:7], off offset:3072 nt
	global_store_dword v114, v129, s[10:11] offset:3584 nt
	global_store_dwordx2 v[38:39], v[12:13], off offset:3584 nt
	global_store_dword v114, v130, s[10:11] offset:3840 nt
	s_add_u32 s10, s10, s12
	s_addc_u32 s11, s11, s13
	s_add_u32 s14, s14, s16
	s_addc_u32 s15, s15, s17
	s_add_u32 s30, s30, s34
	s_addc_u32 s31, s31, s35
	s_cmpk_lt_i32 s6, 0x4000
	s_cbranch_scc1 .LBB0_838

.LBB0_1101:
	v_cmp_lt_i32_e32 vcc, v88, v87
	v_lshl_add_u64 v[2:3], v[12:13], 0, s[12:13]
	s_add_u32 s4, s6, s12
	v_cndmask_b32_e32 v4, v86, v88, vcc
	v_cmp_lt_i32_e32 vcc, v89, v87
	s_addc_u32 s5, s7, s13
	v_lshlrev_b32_e32 v139, 2, v4
	v_cndmask_b32_e32 v5, v86, v89, vcc
	v_cmp_lt_i32_e32 vcc, v90, v87
	v_lshlrev_b32_e32 v142, 2, v5
	s_add_i32 s8, s8, s10
	v_cndmask_b32_e32 v6, v86, v90, vcc
	v_cmp_lt_i32_e32 vcc, v91, v87
	v_lshlrev_b32_e32 v143, 2, v6
	s_add_u32 s6, s6, s14
	v_cndmask_b32_e32 v7, v86, v91, vcc
	v_cmp_lt_i32_e32 vcc, v92, v87
	v_lshlrev_b32_e32 v144, 2, v7
	s_addc_u32 s7, s7, s15
	v_cndmask_b32_e32 v8, v86, v92, vcc
	v_cmp_lt_i32_e32 vcc, v93, v87
	v_lshlrev_b32_e32 v145, 2, v8
	v_lshl_add_u64 v[12:13], v[12:13], 0, s[14:15]
	v_cndmask_b32_e32 v9, v86, v93, vcc
	v_add_co_u32_e32 v18, vcc, s19, v2
	v_lshlrev_b32_e32 v146, 2, v9
	s_nop 0
	v_addc_co_u32_e32 v19, vcc, 0, v3, vcc
	v_add_co_u32_e32 v14, vcc, s24, v2
	s_cmpk_lt_i32 s8, 0x4000
	s_nop 0
	v_addc_co_u32_e32 v15, vcc, 0, v3, vcc
	v_lshl_add_u64 v[2:3], s[4:5], 0, v[10:11]
	v_add_co_u32_e32 v8, vcc, 0x2b200000, v2
	v_lshl_add_u64 v[4:5], v[2:3], 0, s[16:17]
	s_nop 0
	v_addc_co_u32_e32 v9, vcc, 0, v3, vcc
	v_lshl_add_u64 v[6:7], v[2:3], 0, s[30:31]
	v_add_co_u32_e32 v32, vcc, s3, v2
	global_load_dwordx2 v[22:23], v[4:5], off offset:512
	global_load_dwordx2 v[24:25], v[4:5], off offset:1024
	global_load_dwordx2 v[26:27], v[4:5], off offset:1536
	global_load_dwordx2 v[28:29], v[4:5], off offset:2048
	global_load_dwordx2 v[30:31], v[4:5], off offset:2560
	global_load_dwordx2 v[34:35], v[4:5], off offset:3072
	global_load_dwordx2 v[36:37], v[4:5], off offset:3584
	global_load_dwordx2 v[38:39], v[6:7], off offset:512
	global_load_dwordx2 v[40:41], v[6:7], off offset:1024
	global_load_dwordx2 v[42:43], v[6:7], off offset:1536
	global_load_dwordx2 v[44:45], v[6:7], off offset:2048
	global_load_dwordx2 v[46:47], v[6:7], off offset:2560
	global_load_dwordx2 v[48:49], v[6:7], off offset:3072
	global_load_dwordx2 v[50:51], v[8:9], off
	v_addc_co_u32_e32 v33, vcc, 0, v3, vcc
	v_lshl_add_u64 v[20:21], v[2:3], 0, s[34:35]
	v_add_co_u32_e64 v16, s[4:5], s25, v2
	v_add_co_u32_e32 v2, vcc, s9, v2
	global_load_dwordx2 v[52:53], v[32:33], off offset:512
	global_load_dwordx2 v[54:55], v[32:33], off offset:1024
	global_load_dwordx2 v[56:57], v[32:33], off offset:1536
	global_load_dwordx2 v[58:59], v[32:33], off offset:2048
	v_addc_co_u32_e64 v17, s[4:5], 0, v3, s[4:5]
	v_addc_co_u32_e32 v3, vcc, 0, v3, vcc
	global_load_dwordx2 v[60:61], v[32:33], off
	global_load_dwordx2 v[62:63], v[6:7], off offset:3584
	global_load_dwordx2 v[64:65], v[32:33], off offset:2560
	global_load_dwordx2 v[66:67], v[32:33], off offset:3072
	global_load_dwordx2 v[68:69], v[32:33], off offset:3584
	global_load_dwordx2 v[70:71], v[2:3], off offset:-4096
	global_load_dwordx2 v[72:73], v[2:3], off
	global_load_dwordx2 v[74:75], v[2:3], off offset:512
	global_load_dwordx2 v[76:77], v[2:3], off offset:1024
	global_load_dwordx2 v[78:79], v[2:3], off offset:1536
	global_load_dwordx2 v[80:81], v[2:3], off offset:2048
	global_load_dwordx2 v[82:83], v[2:3], off offset:2560
	global_load_dwordx2 v[84:85], v[2:3], off offset:3072
	global_load_dwordx2 v[96:97], v[2:3], off offset:3584
	ds_read_b128 v[2:5], v1
	ds_read_b128 v[6:9], v1 offset:16384
	s_waitcnt vmcnt(26)
	v_lshlrev_b32_e32 v116, 16, v34
	v_lshlrev_b32_e32 v32, 16, v22
	v_and_b32_e32 v33, 0xffff0000, v22
	v_lshlrev_b32_e32 v98, 16, v23
	v_and_b32_e32 v99, 0xffff0000, v23
	v_lshlrev_b32_e32 v100, 16, v24
	v_and_b32_e32 v101, 0xffff0000, v24
	v_lshlrev_b32_e32 v102, 16, v25
	v_and_b32_e32 v103, 0xffff0000, v25
	v_lshlrev_b32_e32 v104, 16, v26
	v_and_b32_e32 v105, 0xffff0000, v26
	v_lshlrev_b32_e32 v106, 16, v27
	v_and_b32_e32 v107, 0xffff0000, v27
	v_lshlrev_b32_e32 v108, 16, v28
	v_and_b32_e32 v109, 0xffff0000, v28
	v_lshlrev_b32_e32 v110, 16, v29
	v_and_b32_e32 v111, 0xffff0000, v29
	v_lshlrev_b32_e32 v112, 16, v30
	v_and_b32_e32 v113, 0xffff0000, v30
	v_lshlrev_b32_e32 v114, 16, v31
	v_and_b32_e32 v115, 0xffff0000, v31
	v_and_b32_e32 v117, 0xffff0000, v34
	v_lshlrev_b32_e32 v118, 16, v35
	v_and_b32_e32 v119, 0xffff0000, v35
	s_waitcnt vmcnt(25)
	v_lshlrev_b32_e32 v120, 16, v36
	v_and_b32_e32 v121, 0xffff0000, v36
	v_lshlrev_b32_e32 v122, 16, v37
	v_and_b32_e32 v123, 0xffff0000, v37
	s_waitcnt vmcnt(18)
	v_lshlrev_b32_e32 v124, 16, v50
	v_and_b32_e32 v50, 0xffff0000, v50
	v_lshlrev_b32_e32 v125, 16, v51
	v_and_b32_e32 v51, 0xffff0000, v51
	v_fma_mix_f32 v22, v38, s11, v32 op_sel_hi:[1,0,0]
	v_fma_mix_f32 v23, v38, s11, v33 op_sel:[1,0,0] op_sel_hi:[1,0,0]
	v_fma_mix_f32 v24, v39, s11, v98 op_sel_hi:[1,0,0]
	v_fma_mix_f32 v25, v39, s11, v99 op_sel:[1,0,0] op_sel_hi:[1,0,0]
	v_fma_mix_f32 v26, v40, s11, v100 op_sel_hi:[1,0,0]
	v_fma_mix_f32 v27, v40, s11, v101 op_sel:[1,0,0] op_sel_hi:[1,0,0]
	v_fma_mix_f32 v28, v41, s11, v102 op_sel_hi:[1,0,0]
	v_fma_mix_f32 v29, v41, s11, v103 op_sel:[1,0,0] op_sel_hi:[1,0,0]
	v_fma_mix_f32 v30, v42, s11, v104 op_sel_hi:[1,0,0]
	v_fma_mix_f32 v31, v42, s11, v105 op_sel:[1,0,0] op_sel_hi:[1,0,0]
	v_fma_mix_f32 v32, v43, s11, v106 op_sel_hi:[1,0,0]
	v_fma_mix_f32 v33, v43, s11, v107 op_sel:[1,0,0] op_sel_hi:[1,0,0]
	v_fma_mix_f32 v34, v44, s11, v108 op_sel_hi:[1,0,0]
	v_fma_mix_f32 v35, v44, s11, v109 op_sel:[1,0,0] op_sel_hi:[1,0,0]
	v_fma_mix_f32 v36, v45, s11, v110 op_sel_hi:[1,0,0]
	v_fma_mix_f32 v37, v45, s11, v111 op_sel:[1,0,0] op_sel_hi:[1,0,0]
	v_fma_mix_f32 v38, v46, s11, v112 op_sel_hi:[1,0,0]
	v_fma_mix_f32 v39, v46, s11, v113 op_sel:[1,0,0] op_sel_hi:[1,0,0]
	v_fma_mix_f32 v40, v47, s11, v114 op_sel_hi:[1,0,0]
	v_fma_mix_f32 v41, v47, s11, v115 op_sel:[1,0,0] op_sel_hi:[1,0,0]
	v_fma_mix_f32 v42, v48, s11, v116 op_sel_hi:[1,0,0]
	v_fma_mix_f32 v43, v48, s11, v117 op_sel:[1,0,0] op_sel_hi:[1,0,0]
	v_fma_mix_f32 v44, v49, s11, v118 op_sel_hi:[1,0,0]
	v_fma_mix_f32 v45, v49, s11, v119 op_sel:[1,0,0] op_sel_hi:[1,0,0]
	s_waitcnt vmcnt(12)
	v_fma_mix_f32 v46, v62, s11, v120 op_sel_hi:[1,0,0]
	v_fma_mix_f32 v47, v62, s11, v121 op_sel:[1,0,0] op_sel_hi:[1,0,0]
	v_fma_mix_f32 v48, v63, s11, v122 op_sel_hi:[1,0,0]
	v_fma_mix_f32 v49, v63, s11, v123 op_sel:[1,0,0] op_sel_hi:[1,0,0]
	v_lshlrev_b32_e32 v62, 16, v60
	v_and_b32_e32 v63, 0xffff0000, v60
	v_lshlrev_b32_e32 v110, 16, v61
	v_and_b32_e32 v111, 0xffff0000, v61
	v_lshlrev_b32_e32 v112, 16, v52
	v_and_b32_e32 v113, 0xffff0000, v52
	v_lshlrev_b32_e32 v114, 16, v53
	v_and_b32_e32 v115, 0xffff0000, v53
	v_lshlrev_b32_e32 v116, 16, v54
	v_and_b32_e32 v117, 0xffff0000, v54
	v_lshlrev_b32_e32 v118, 16, v55
	v_and_b32_e32 v119, 0xffff0000, v55
	v_lshlrev_b32_e32 v120, 16, v56
	v_and_b32_e32 v121, 0xffff0000, v56
	v_lshlrev_b32_e32 v122, 16, v57
	v_and_b32_e32 v123, 0xffff0000, v57
	v_lshlrev_b32_e32 v126, 16, v58
	v_and_b32_e32 v127, 0xffff0000, v58
	v_lshlrev_b32_e32 v128, 16, v59
	v_and_b32_e32 v129, 0xffff0000, v59
	s_waitcnt vmcnt(11)
	v_lshlrev_b32_e32 v130, 16, v64
	v_and_b32_e32 v131, 0xffff0000, v64
	v_lshlrev_b32_e32 v132, 16, v65
	v_and_b32_e32 v133, 0xffff0000, v65
	s_waitcnt vmcnt(10)
	v_lshlrev_b32_e32 v134, 16, v66
	v_and_b32_e32 v135, 0xffff0000, v66
	v_lshlrev_b32_e32 v136, 16, v67
	v_and_b32_e32 v137, 0xffff0000, v67
	s_waitcnt vmcnt(9)
	v_lshlrev_b32_e32 v138, 16, v68
	v_and_b32_e32 v140, 0xffff0000, v68
	v_lshlrev_b32_e32 v141, 16, v69
	v_and_b32_e32 v147, 0xffff0000, v69
	s_waitcnt vmcnt(8)
	v_fma_mix_f32 v60, v70, s11, v124 op_sel_hi:[1,0,0]
	v_fma_mix_f32 v61, v70, s11, v50 op_sel:[1,0,0] op_sel_hi:[1,0,0]
	v_fma_mix_f32 v64, v71, s11, v125 op_sel_hi:[1,0,0]
	v_fma_mix_f32 v65, v71, s11, v51 op_sel:[1,0,0] op_sel_hi:[1,0,0]
	s_waitcnt vmcnt(7)
	v_fma_mix_f32 v50, v72, s11, v62 op_sel_hi:[1,0,0]
	v_fma_mix_f32 v51, v72, s11, v63 op_sel:[1,0,0] op_sel_hi:[1,0,0]
	v_fma_mix_f32 v52, v73, s11, v110 op_sel_hi:[1,0,0]
	v_fma_mix_f32 v53, v73, s11, v111 op_sel:[1,0,0] op_sel_hi:[1,0,0]
	s_waitcnt vmcnt(6)
	v_fma_mix_f32 v54, v74, s11, v112 op_sel_hi:[1,0,0]
	v_fma_mix_f32 v55, v74, s11, v113 op_sel:[1,0,0] op_sel_hi:[1,0,0]
	v_fma_mix_f32 v56, v75, s11, v114 op_sel_hi:[1,0,0]
	v_fma_mix_f32 v57, v75, s11, v115 op_sel:[1,0,0] op_sel_hi:[1,0,0]
	s_waitcnt vmcnt(5)
	v_fma_mix_f32 v58, v76, s11, v116 op_sel_hi:[1,0,0]
	v_fma_mix_f32 v59, v76, s11, v117 op_sel:[1,0,0] op_sel_hi:[1,0,0]
	v_fma_mix_f32 v62, v77, s11, v118 op_sel_hi:[1,0,0]
	v_fma_mix_f32 v63, v77, s11, v119 op_sel:[1,0,0] op_sel_hi:[1,0,0]
	s_waitcnt vmcnt(4)
	v_fma_mix_f32 v66, v78, s11, v120 op_sel_hi:[1,0,0]
	v_fma_mix_f32 v67, v78, s11, v121 op_sel:[1,0,0] op_sel_hi:[1,0,0]
	v_fma_mix_f32 v68, v79, s11, v122 op_sel_hi:[1,0,0]
	v_fma_mix_f32 v69, v79, s11, v123 op_sel:[1,0,0] op_sel_hi:[1,0,0]
	s_waitcnt vmcnt(3)
	v_fma_mix_f32 v70, v80, s11, v126 op_sel_hi:[1,0,0]
	v_fma_mix_f32 v71, v80, s11, v127 op_sel:[1,0,0] op_sel_hi:[1,0,0]
	v_fma_mix_f32 v72, v81, s11, v128 op_sel_hi:[1,0,0]
	v_fma_mix_f32 v73, v81, s11, v129 op_sel:[1,0,0] op_sel_hi:[1,0,0]
	s_waitcnt vmcnt(2)
	v_fma_mix_f32 v74, v82, s11, v130 op_sel_hi:[1,0,0]
	v_fma_mix_f32 v75, v82, s11, v131 op_sel:[1,0,0] op_sel_hi:[1,0,0]
	v_fma_mix_f32 v76, v83, s11, v132 op_sel_hi:[1,0,0]
	v_fma_mix_f32 v77, v83, s11, v133 op_sel:[1,0,0] op_sel_hi:[1,0,0]
	s_waitcnt vmcnt(1)
	v_fma_mix_f32 v78, v84, s11, v134 op_sel_hi:[1,0,0]
	v_fma_mix_f32 v79, v84, s11, v135 op_sel:[1,0,0] op_sel_hi:[1,0,0]
	v_fma_mix_f32 v80, v85, s11, v136 op_sel_hi:[1,0,0]
	v_fma_mix_f32 v81, v85, s11, v137 op_sel:[1,0,0] op_sel_hi:[1,0,0]
	s_waitcnt vmcnt(0)
	v_fma_mix_f32 v82, v96, s11, v138 op_sel_hi:[1,0,0]
	v_fma_mix_f32 v83, v96, s11, v140 op_sel:[1,0,0] op_sel_hi:[1,0,0]
	v_fma_mix_f32 v84, v97, s11, v141 op_sel_hi:[1,0,0]
	v_fma_mix_f32 v85, v97, s11, v147 op_sel:[1,0,0] op_sel_hi:[1,0,0]
	v_add_f32_e32 v96, v60, v61
	v_add_f32_e32 v97, v64, v65
	v_add_f32_e32 v98, v22, v23
	v_add_f32_e32 v99, v24, v25
	v_add_f32_e32 v96, v96, v97
	v_add_f32_e32 v100, v26, v27
	v_add_f32_e32 v101, v28, v29
	v_add_f32_e32 v98, v98, v99
	v_add_f32_e32 v96, 0, v96
	v_add_f32_e32 v102, v30, v31
	v_add_f32_e32 v103, v32, v33
	v_add_f32_e32 v99, v100, v101
	v_add_f32_e32 v96, v96, v98
	v_add_f32_e32 v104, v34, v35
	v_add_f32_e32 v105, v36, v37
	v_add_f32_e32 v100, v102, v103
	v_add_f32_e32 v96, v96, v99
	v_add_f32_e32 v106, v38, v39
	v_add_f32_e32 v107, v40, v41
	v_add_f32_e32 v101, v104, v105
	v_add_f32_e32 v96, v96, v100
	v_add_f32_e32 v108, v42, v43
	v_add_f32_e32 v109, v44, v45
	v_add_f32_e32 v102, v106, v107
	v_add_f32_e32 v96, v96, v101
	v_add_f32_e32 v103, v108, v109
	v_add_f32_e32 v104, v46, v47
	v_add_f32_e32 v105, v48, v49
	v_add_f32_e32 v96, v96, v102
	v_add_f32_e32 v104, v104, v105
	v_add_f32_e32 v105, v50, v51
	v_add_f32_e32 v106, v52, v53
	v_add_f32_e32 v96, v96, v103
	v_add_f32_e32 v107, v54, v55
	v_add_f32_e32 v108, v56, v57
	v_add_f32_e32 v97, v105, v106
	v_add_f32_e32 v96, v96, v104
	v_add_f32_e32 v109, v58, v59
	v_add_f32_e32 v110, v62, v63
	v_add_f32_e32 v105, v107, v108
	v_add_f32_e32 v96, v96, v97
	v_add_f32_e32 v111, v66, v67
	v_add_f32_e32 v112, v68, v69
	v_add_f32_e32 v106, v109, v110
	v_add_f32_e32 v96, v96, v105
	v_add_f32_e32 v113, v70, v71
	v_add_f32_e32 v114, v72, v73
	v_add_f32_e32 v107, v111, v112
	v_add_f32_e32 v96, v96, v106
	v_add_f32_e32 v115, v74, v75
	v_add_f32_e32 v116, v76, v77
	v_add_f32_e32 v108, v113, v114
	v_add_f32_e32 v96, v96, v107
	v_add_f32_e32 v117, v78, v79
	v_add_f32_e32 v118, v80, v81
	v_add_f32_e32 v109, v115, v116
	v_add_f32_e32 v96, v96, v108
	v_add_f32_e32 v119, v82, v83
	v_add_f32_e32 v120, v84, v85
	v_add_f32_e32 v110, v117, v118
	v_add_f32_e32 v96, v96, v109
	v_add_f32_e32 v111, v119, v120
	v_add_f32_e32 v96, v96, v110
	v_add_f32_e32 v96, v96, v111
	ds_bpermute_b32 v97, v139, v96
	s_waitcnt lgkmcnt(0)
	v_add_f32_e32 v96, v96, v97
	ds_bpermute_b32 v97, v142, v96
	s_waitcnt lgkmcnt(0)
	v_add_f32_e32 v96, v96, v97
	ds_bpermute_b32 v97, v143, v96
	s_waitcnt lgkmcnt(0)
	v_add_f32_e32 v96, v96, v97
	ds_bpermute_b32 v97, v144, v96
	s_waitcnt lgkmcnt(0)
	v_add_f32_e32 v96, v96, v97
	ds_bpermute_b32 v97, v145, v96
	s_waitcnt lgkmcnt(0)
	v_add_f32_e32 v96, v96, v97
	ds_bpermute_b32 v97, v146, v96
	s_waitcnt lgkmcnt(0)
	v_add_f32_e32 v96, v96, v97
	v_fmac_f32_e32 v61, 0xb9800000, v96
	v_fmac_f32_e32 v60, 0xb9800000, v96
	v_fmac_f32_e32 v65, 0xb9800000, v96
	v_fmac_f32_e32 v64, 0xb9800000, v96
	v_fmac_f32_e32 v23, 0xb9800000, v96
	v_fmac_f32_e32 v22, 0xb9800000, v96
	v_fmac_f32_e32 v25, 0xb9800000, v96
	v_fmac_f32_e32 v24, 0xb9800000, v96
	v_fmac_f32_e32 v27, 0xb9800000, v96
	v_fmac_f32_e32 v26, 0xb9800000, v96
	v_fmac_f32_e32 v29, 0xb9800000, v96
	v_fmac_f32_e32 v28, 0xb9800000, v96
	v_fmac_f32_e32 v33, 0xb9800000, v96
	v_fmac_f32_e32 v32, 0xb9800000, v96
	v_fmac_f32_e32 v31, 0xb9800000, v96
	v_fmac_f32_e32 v30, 0xb9800000, v96
	v_fmac_f32_e32 v35, 0xb9800000, v96
	v_fmac_f32_e32 v34, 0xb9800000, v96
	v_fmac_f32_e32 v37, 0xb9800000, v96
	v_fmac_f32_e32 v36, 0xb9800000, v96
	v_fmac_f32_e32 v39, 0xb9800000, v96
	v_fmac_f32_e32 v38, 0xb9800000, v96
	v_fmac_f32_e32 v41, 0xb9800000, v96
	v_fmac_f32_e32 v40, 0xb9800000, v96
	v_fmac_f32_e32 v45, 0xb9800000, v96
	v_fmac_f32_e32 v44, 0xb9800000, v96
	v_fmac_f32_e32 v43, 0xb9800000, v96
	v_fmac_f32_e32 v42, 0xb9800000, v96
	v_fmac_f32_e32 v47, 0xb9800000, v96
	v_fmac_f32_e32 v46, 0xb9800000, v96
	v_fmac_f32_e32 v49, 0xb9800000, v96
	v_fmac_f32_e32 v48, 0xb9800000, v96
	v_fmac_f32_e32 v51, 0xb9800000, v96
	v_fmac_f32_e32 v50, 0xb9800000, v96
	v_fmac_f32_e32 v53, 0xb9800000, v96
	v_fmac_f32_e32 v52, 0xb9800000, v96
	v_fmac_f32_e32 v57, 0xb9800000, v96
	v_fmac_f32_e32 v56, 0xb9800000, v96
	v_fmac_f32_e32 v55, 0xb9800000, v96
	v_fmac_f32_e32 v54, 0xb9800000, v96
	v_fmac_f32_e32 v59, 0xb9800000, v96
	v_fmac_f32_e32 v58, 0xb9800000, v96
	v_fmac_f32_e32 v63, 0xb9800000, v96
	v_fmac_f32_e32 v62, 0xb9800000, v96
	v_fmac_f32_e32 v67, 0xb9800000, v96
	v_fmac_f32_e32 v66, 0xb9800000, v96
	v_fmac_f32_e32 v69, 0xb9800000, v96
	v_fmac_f32_e32 v68, 0xb9800000, v96
	v_fmac_f32_e32 v73, 0xb9800000, v96
	v_fmac_f32_e32 v72, 0xb9800000, v96
	v_fmac_f32_e32 v71, 0xb9800000, v96
	v_fmac_f32_e32 v70, 0xb9800000, v96
	v_fmac_f32_e32 v75, 0xb9800000, v96
	v_fmac_f32_e32 v74, 0xb9800000, v96
	v_fmac_f32_e32 v77, 0xb9800000, v96
	v_fmac_f32_e32 v76, 0xb9800000, v96
	v_fmac_f32_e32 v79, 0xb9800000, v96
	v_fmac_f32_e32 v78, 0xb9800000, v96
	v_fmac_f32_e32 v81, 0xb9800000, v96
	v_fmac_f32_e32 v80, 0xb9800000, v96
	v_fmac_f32_e32 v85, 0xb9800000, v96
	v_fmac_f32_e32 v84, 0xb9800000, v96
	v_fmac_f32_e32 v83, 0xb9800000, v96
	v_fmac_f32_e32 v82, 0xb9800000, v96
	v_pk_mul_f32 v[96:97], v[64:65], v[64:65]
	v_pk_mul_f32 v[98:99], v[60:61], v[60:61]
	v_pk_mul_f32 v[100:101], v[24:25], v[24:25]
	v_pk_mul_f32 v[102:103], v[22:23], v[22:23]
	v_pk_mov_b32 v[140:141], v[98:99], v[96:97] op_sel:[1,0]
	v_mov_b32_e32 v99, v97
	v_pk_mov_b32 v[96:97], v[102:103], v[100:101] op_sel:[1,0]
	v_mov_b32_e32 v103, v101
	v_mul_f32_e32 v104, v26, v26
	v_mul_f32_e32 v106, v28, v28
	v_pk_add_f32 v[98:99], v[140:141], v[98:99]
	v_pk_add_f32 v[96:97], v[96:97], v[102:103]
	v_pk_fma_f32 v[100:101], v[26:27], v[26:27], v[104:105] op_sel_hi:[1,1,0]
	v_pk_fma_f32 v[104:105], v[28:29], v[28:29], v[106:107] op_sel_hi:[1,1,0]
	v_pk_add_f32 v[98:99], v[98:99], v[98:99] op_sel_hi:[0,1]
	v_pk_add_f32 v[96:97], v[96:97], v[96:97] op_sel_hi:[0,1]
	v_pk_mul_f32 v[108:109], v[36:37], v[36:37]
	v_pk_mul_f32 v[110:111], v[34:35], v[34:35]
	v_mul_f32_e32 v100, v30, v30
	v_mul_f32_e32 v104, v31, v31
	v_mul_f32_e32 v98, v32, v32
	v_mul_f32_e32 v96, v33, v33
	v_pk_mov_b32 v[106:107], v[110:111], v[108:109] op_sel:[1,0]
	v_mov_b32_e32 v111, v109
	v_pk_add_f32 v[100:101], v[100:101], v[104:105]
	v_pk_add_f32 v[96:97], v[98:99], v[96:97]
	v_mul_f32_e32 v112, v38, v38
	v_mul_f32_e32 v114, v40, v40
	v_pk_add_f32 v[102:103], v[106:107], v[110:111]
	v_pk_add_f32 v[96:97], v[100:101], v[96:97]
	v_pk_fma_f32 v[108:109], v[38:39], v[38:39], v[112:113] op_sel_hi:[1,1,0]
	v_pk_fma_f32 v[112:113], v[40:41], v[40:41], v[114:115] op_sel_hi:[1,1,0]
	v_pk_add_f32 v[102:103], v[102:103], v[102:103] op_sel_hi:[0,1]
	v_pk_add_f32 v[96:97], v[96:97], v[96:97] op_sel_hi:[0,1]
	v_pk_mul_f32 v[116:117], v[48:49], v[48:49]
	v_pk_mul_f32 v[118:119], v[46:47], v[46:47]
	v_mul_f32_e32 v108, v42, v42
	v_mul_f32_e32 v112, v43, v43
	v_mul_f32_e32 v102, v44, v44
	v_mul_f32_e32 v96, v45, v45
	v_pk_mov_b32 v[114:115], v[118:119], v[116:117] op_sel:[1,0]
	v_mov_b32_e32 v119, v117
	v_pk_add_f32 v[104:105], v[108:109], v[112:113]
	v_pk_add_f32 v[96:97], v[102:103], v[96:97]
	v_mul_f32_e32 v120, v50, v50
	v_mul_f32_e32 v122, v52, v52
	v_pk_add_f32 v[106:107], v[114:115], v[118:119]
	v_pk_add_f32 v[96:97], v[104:105], v[96:97]
	v_pk_fma_f32 v[116:117], v[50:51], v[50:51], v[120:121] op_sel_hi:[1,1,0]
	v_pk_fma_f32 v[120:121], v[52:53], v[52:53], v[122:123] op_sel_hi:[1,1,0]
	v_pk_add_f32 v[106:107], v[106:107], v[106:107] op_sel_hi:[0,1]
	v_pk_add_f32 v[96:97], v[96:97], v[96:97] op_sel_hi:[0,1]
	v_pk_mul_f32 v[124:125], v[62:63], v[62:63]
	v_pk_mul_f32 v[126:127], v[58:59], v[58:59]
	v_mul_f32_e32 v116, v54, v54
	v_mul_f32_e32 v120, v55, v55
	v_mul_f32_e32 v106, v56, v56
	v_mul_f32_e32 v96, v57, v57
	v_pk_mov_b32 v[122:123], v[126:127], v[124:125] op_sel:[1,0]
	v_mov_b32_e32 v127, v125
	v_pk_add_f32 v[108:109], v[116:117], v[120:121]
	v_pk_add_f32 v[96:97], v[106:107], v[96:97]
	v_mul_f32_e32 v128, v66, v66
	v_mul_f32_e32 v130, v68, v68
	v_pk_add_f32 v[110:111], v[122:123], v[126:127]
	v_pk_add_f32 v[96:97], v[108:109], v[96:97]
	v_pk_fma_f32 v[124:125], v[66:67], v[66:67], v[128:129] op_sel_hi:[1,1,0]
	v_pk_fma_f32 v[128:129], v[68:69], v[68:69], v[130:131] op_sel_hi:[1,1,0]
	v_pk_add_f32 v[110:111], v[110:111], v[110:111] op_sel_hi:[0,1]
	v_pk_add_f32 v[96:97], v[96:97], v[96:97] op_sel_hi:[0,1]
	v_pk_mul_f32 v[132:133], v[76:77], v[76:77]
	v_pk_mul_f32 v[134:135], v[74:75], v[74:75]
	v_mul_f32_e32 v124, v70, v70
	v_mul_f32_e32 v128, v71, v71
	v_mul_f32_e32 v110, v72, v72
	v_mul_f32_e32 v96, v73, v73
	v_pk_mov_b32 v[130:131], v[134:135], v[132:133] op_sel:[1,0]
	v_mov_b32_e32 v135, v133
	v_pk_add_f32 v[112:113], v[124:125], v[128:129]
	v_pk_add_f32 v[96:97], v[110:111], v[96:97]
	v_mul_f32_e32 v136, v78, v78
	v_mul_f32_e32 v138, v80, v80
	v_pk_add_f32 v[114:115], v[130:131], v[134:135]
	v_pk_add_f32 v[96:97], v[112:113], v[96:97]
	v_pk_fma_f32 v[132:133], v[78:79], v[78:79], v[136:137] op_sel_hi:[1,1,0]
	v_pk_fma_f32 v[136:137], v[80:81], v[80:81], v[138:139] op_sel_hi:[1,1,0]
	v_pk_add_f32 v[114:115], v[114:115], v[114:115] op_sel_hi:[0,1]
	v_pk_add_f32 v[96:97], v[96:97], v[96:97] op_sel_hi:[0,1]
	v_mul_f32_e32 v132, v82, v82
	v_mul_f32_e32 v136, v83, v83
	v_mul_f32_e32 v114, v84, v84
	v_mul_f32_e32 v96, v85, v85
	v_pk_add_f32 v[116:117], v[132:133], v[136:137]
	v_pk_add_f32 v[96:97], v[114:115], v[96:97]
	s_nop 0
	v_pk_add_f32 v[96:97], v[116:117], v[96:97]
	s_nop 0
	v_add_f32_e32 v96, v96, v97
	ds_bpermute_b32 v97, v139, v96
	s_waitcnt lgkmcnt(0)
	v_add_f32_e32 v96, v96, v97
	ds_bpermute_b32 v97, v142, v96
	s_waitcnt lgkmcnt(0)
	v_add_f32_e32 v96, v96, v97
	ds_bpermute_b32 v97, v143, v96
	s_waitcnt lgkmcnt(0)
	v_add_f32_e32 v96, v96, v97
	ds_bpermute_b32 v97, v144, v96
	s_waitcnt lgkmcnt(0)
	v_add_f32_e32 v96, v96, v97
	ds_bpermute_b32 v97, v145, v96
	s_waitcnt lgkmcnt(0)
	v_add_f32_e32 v96, v96, v97
	ds_bpermute_b32 v97, v146, v96
	s_waitcnt lgkmcnt(0)
	v_add_f32_e32 v96, v96, v97
	v_fmamk_f32 v96, v96, 0x39800000, v94
	v_mul_f32_e32 v97, 0x4f800000, v96
	v_cmp_gt_f32_e32 vcc, s18, v96
	s_nop 1
	v_cndmask_b32_e32 v96, v96, v97, vcc
	v_sqrt_f32_e32 v97, v96
	s_nop 0
	v_add_u32_e32 v98, -1, v97
	v_add_u32_e32 v99, 1, v97
	v_fma_f32 v100, -v98, v97, v96
	v_fma_f32 v101, -v99, v97, v96
	v_cmp_ge_f32_e64 s[4:5], 0, v100
	s_nop 1
	v_cndmask_b32_e64 v97, v97, v98, s[4:5]
	v_cmp_lt_f32_e64 s[4:5], 0, v101
	s_nop 1
	v_cndmask_b32_e64 v97, v97, v99, s[4:5]
	v_mul_f32_e32 v98, 0x37800000, v97
	v_cndmask_b32_e32 v97, v97, v98, vcc
	v_cmp_class_f32_e32 vcc, v96, v95
	s_nop 1
	v_cndmask_b32_e32 v96, v97, v96, vcc
	v_div_scale_f32 v97, s[4:5], v96, v96, 1.0
	v_rcp_f32_e32 v99, v97
	v_div_scale_f32 v98, vcc, 1.0, v96, 1.0
	v_fma_f32 v100, -v97, v99, 1.0
	v_fmac_f32_e32 v99, v100, v99
	v_mul_f32_e32 v100, v98, v99
	v_fma_f32 v101, -v97, v100, v98
	v_fmac_f32_e32 v100, v101, v99
	v_fma_f32 v97, -v97, v100, v98
	v_div_fmas_f32 v97, v97, v99, v100
	v_div_fixup_f32 v96, v97, v96, 1.0
	v_pk_mul_f32 v[60:61], v[60:61], v[96:97] op_sel_hi:[1,0]
	v_pk_mul_f32 v[64:65], v[64:65], v[96:97] op_sel_hi:[1,0]
	v_pk_fma_f32 v[2:3], v[2:3], v[60:61], v[6:7]
	v_pk_fma_f32 v[4:5], v[4:5], v[64:65], v[8:9]
	v_cvt_pk_f16_f32 v6, v2, v3
	v_cvt_pk_f16_f32 v7, v4, v5
	global_store_dwordx2 v[14:15], v[6:7], off offset:-4096 nt
	v_cvt_pk_bf16_f32 v60, v2, v3
	v_cvt_pk_bf16_f32 v61, v4, v5
	ds_read_b128 v[2:5], v1 offset:1024
	ds_read_b128 v[6:9], v1 offset:17408
	v_pk_mul_f32 v[22:23], v[22:23], v[96:97] op_sel_hi:[1,0]
	v_pk_mul_f32 v[24:25], v[24:25], v[96:97] op_sel_hi:[1,0]
	global_store_dwordx2 v[16:17], v[60:61], off offset:-4096 nt
	v_pk_mul_f32 v[26:27], v[26:27], v[96:97] op_sel_hi:[1,0]
	s_waitcnt lgkmcnt(0)
	v_pk_fma_f32 v[4:5], v[4:5], v[24:25], v[8:9]
	v_pk_fma_f32 v[2:3], v[2:3], v[22:23], v[6:7]
	v_cvt_pk_f16_f32 v7, v4, v5
	v_cvt_pk_f16_f32 v6, v2, v3
	global_store_dwordx2 v[18:19], v[6:7], off offset:512 nt
	v_cvt_pk_bf16_f32 v22, v2, v3
	v_cvt_pk_bf16_f32 v23, v4, v5
	ds_read_b128 v[2:5], v1 offset:2048
	ds_read_b128 v[6:9], v1 offset:18432
	v_pk_mul_f32 v[28:29], v[28:29], v[96:97] op_sel_hi:[1,0]
	global_store_dwordx2 v[20:21], v[22:23], off offset:512 nt
	v_pk_mul_f32 v[30:31], v[30:31], v[96:97] op_sel_hi:[1,0]
	v_pk_mul_f32 v[32:33], v[32:33], v[96:97] op_sel_hi:[1,0]
	s_waitcnt lgkmcnt(0)
	v_pk_fma_f32 v[4:5], v[4:5], v[28:29], v[8:9]
	v_pk_fma_f32 v[2:3], v[2:3], v[26:27], v[6:7]
	v_cvt_pk_f16_f32 v7, v4, v5
	v_cvt_pk_f16_f32 v6, v2, v3
	global_store_dwordx2 v[18:19], v[6:7], off offset:1024 nt
	v_cvt_pk_bf16_f32 v22, v2, v3
	v_cvt_pk_bf16_f32 v23, v4, v5
	ds_read_b128 v[2:5], v1 offset:3072
	ds_read_b128 v[6:9], v1 offset:19456
	global_store_dwordx2 v[20:21], v[22:23], off offset:1024 nt
	v_pk_mul_f32 v[34:35], v[34:35], v[96:97] op_sel_hi:[1,0]
	v_pk_mul_f32 v[36:37], v[36:37], v[96:97] op_sel_hi:[1,0]
	v_pk_mul_f32 v[38:39], v[38:39], v[96:97] op_sel_hi:[1,0]
	s_waitcnt lgkmcnt(0)
	v_pk_fma_f32 v[4:5], v[4:5], v[32:33], v[8:9]
	v_pk_fma_f32 v[2:3], v[2:3], v[30:31], v[6:7]
	v_cvt_pk_f16_f32 v7, v4, v5
	v_cvt_pk_f16_f32 v6, v2, v3
	global_store_dwordx2 v[18:19], v[6:7], off offset:1536 nt
	v_cvt_pk_bf16_f32 v2, v2, v3
	v_cvt_pk_bf16_f32 v3, v4, v5
	global_store_dwordx2 v[20:21], v[2:3], off offset:1536 nt
	ds_read_b128 v[2:5], v1 offset:4096
	ds_read_b128 v[6:9], v1 offset:20480
	v_pk_mul_f32 v[40:41], v[40:41], v[96:97] op_sel_hi:[1,0]
	v_pk_mul_f32 v[42:43], v[42:43], v[96:97] op_sel_hi:[1,0]
	v_pk_mul_f32 v[44:45], v[44:45], v[96:97] op_sel_hi:[1,0]
	v_pk_mul_f32 v[46:47], v[46:47], v[96:97] op_sel_hi:[1,0]
	s_waitcnt lgkmcnt(0)
	v_pk_fma_f32 v[4:5], v[4:5], v[36:37], v[8:9]
	v_pk_fma_f32 v[2:3], v[2:3], v[34:35], v[6:7]
	v_cvt_pk_f16_f32 v7, v4, v5
	v_cvt_pk_f16_f32 v6, v2, v3
	global_store_dwordx2 v[18:19], v[6:7], off offset:2048 nt
	v_cvt_pk_bf16_f32 v22, v2, v3
	v_cvt_pk_bf16_f32 v23, v4, v5
	ds_read_b128 v[2:5], v1 offset:5120
	ds_read_b128 v[6:9], v1 offset:21504
	global_store_dwordx2 v[20:21], v[22:23], off offset:2048 nt
	v_pk_mul_f32 v[48:49], v[48:49], v[96:97] op_sel_hi:[1,0]
	v_pk_mul_f32 v[50:51], v[50:51], v[96:97] op_sel_hi:[1,0]
	v_pk_mul_f32 v[52:53], v[52:53], v[96:97] op_sel_hi:[1,0]
	s_waitcnt lgkmcnt(0)
	v_pk_fma_f32 v[4:5], v[4:5], v[40:41], v[8:9]
	v_pk_fma_f32 v[2:3], v[2:3], v[38:39], v[6:7]
	v_cvt_pk_f16_f32 v7, v4, v5
	v_cvt_pk_f16_f32 v6, v2, v3
	global_store_dwordx2 v[18:19], v[6:7], off offset:2560 nt
	v_cvt_pk_bf16_f32 v22, v2, v3
	v_cvt_pk_bf16_f32 v23, v4, v5
	ds_read_b128 v[2:5], v1 offset:6144
	ds_read_b128 v[6:9], v1 offset:22528
	global_store_dwordx2 v[20:21], v[22:23], off offset:2560 nt
	v_pk_mul_f32 v[54:55], v[54:55], v[96:97] op_sel_hi:[1,0]
	v_pk_mul_f32 v[56:57], v[56:57], v[96:97] op_sel_hi:[1,0]
	v_pk_mul_f32 v[58:59], v[58:59], v[96:97] op_sel_hi:[1,0]
	s_waitcnt lgkmcnt(0)
	v_pk_fma_f32 v[4:5], v[44:45], v[4:5], v[8:9]
	v_pk_fma_f32 v[2:3], v[42:43], v[2:3], v[6:7]
	v_cvt_pk_f16_f32 v7, v4, v5
	v_cvt_pk_f16_f32 v6, v2, v3
	global_store_dwordx2 v[18:19], v[6:7], off offset:3072 nt
	v_cvt_pk_bf16_f32 v22, v2, v3
	v_cvt_pk_bf16_f32 v23, v4, v5
	ds_read_b128 v[2:5], v1 offset:7168
	ds_read_b128 v[6:9], v1 offset:23552
	global_store_dwordx2 v[20:21], v[22:23], off offset:3072 nt
	v_pk_mul_f32 v[62:63], v[62:63], v[96:97] op_sel_hi:[1,0]
	v_pk_mul_f32 v[66:67], v[66:67], v[96:97] op_sel_hi:[1,0]
	v_pk_mul_f32 v[68:69], v[68:69], v[96:97] op_sel_hi:[1,0]
	s_waitcnt lgkmcnt(0)
	v_pk_fma_f32 v[4:5], v[48:49], v[4:5], v[8:9]
	v_pk_fma_f32 v[2:3], v[46:47], v[2:3], v[6:7]
	v_cvt_pk_f16_f32 v7, v4, v5
	v_cvt_pk_f16_f32 v6, v2, v3
	global_store_dwordx2 v[18:19], v[6:7], off offset:3584 nt
	v_cvt_pk_bf16_f32 v2, v2, v3
	v_cvt_pk_bf16_f32 v3, v4, v5
	global_store_dwordx2 v[20:21], v[2:3], off offset:3584 nt
	ds_read_b128 v[2:5], v1 offset:8192
	ds_read_b128 v[6:9], v1 offset:24576
	v_pk_mul_f32 v[70:71], v[70:71], v[96:97] op_sel_hi:[1,0]
	v_pk_mul_f32 v[72:73], v[72:73], v[96:97] op_sel_hi:[1,0]
	v_pk_mul_f32 v[74:75], v[74:75], v[96:97] op_sel_hi:[1,0]
	v_pk_mul_f32 v[76:77], v[76:77], v[96:97] op_sel_hi:[1,0]
	s_waitcnt lgkmcnt(0)
	v_pk_fma_f32 v[4:5], v[52:53], v[4:5], v[8:9]
	v_pk_fma_f32 v[2:3], v[50:51], v[2:3], v[6:7]
	v_cvt_pk_f16_f32 v7, v4, v5
	v_cvt_pk_f16_f32 v6, v2, v3
	global_store_dwordx2 v[14:15], v[6:7], off nt
	v_cvt_pk_bf16_f32 v18, v2, v3
	v_cvt_pk_bf16_f32 v19, v4, v5
	ds_read_b128 v[2:5], v1 offset:9216
	ds_read_b128 v[6:9], v1 offset:25600
	global_store_dwordx2 v[16:17], v[18:19], off nt
	v_pk_mul_f32 v[78:79], v[78:79], v[96:97] op_sel_hi:[1,0]
	v_pk_mul_f32 v[80:81], v[80:81], v[96:97] op_sel_hi:[1,0]
	v_pk_mul_f32 v[82:83], v[82:83], v[96:97] op_sel_hi:[1,0]
	s_waitcnt lgkmcnt(0)
	v_pk_fma_f32 v[4:5], v[56:57], v[4:5], v[8:9]
	v_pk_fma_f32 v[2:3], v[54:55], v[2:3], v[6:7]
	v_cvt_pk_f16_f32 v7, v4, v5
	v_cvt_pk_f16_f32 v6, v2, v3
	global_store_dwordx2 v[14:15], v[6:7], off offset:512 nt
	v_cvt_pk_bf16_f32 v18, v2, v3
	v_cvt_pk_bf16_f32 v19, v4, v5
	ds_read_b128 v[2:5], v1 offset:10240
	ds_read_b128 v[6:9], v1 offset:26624
	global_store_dwordx2 v[16:17], v[18:19], off offset:512 nt
	v_pk_mul_f32 v[84:85], v[84:85], v[96:97] op_sel_hi:[1,0]
	s_waitcnt lgkmcnt(0)
	v_pk_fma_f32 v[4:5], v[62:63], v[4:5], v[8:9]
	v_pk_fma_f32 v[2:3], v[58:59], v[2:3], v[6:7]
	v_cvt_pk_f16_f32 v7, v4, v5
	v_cvt_pk_f16_f32 v6, v2, v3
	global_store_dwordx2 v[14:15], v[6:7], off offset:1024 nt
	v_cvt_pk_bf16_f32 v18, v2, v3
	v_cvt_pk_bf16_f32 v19, v4, v5
	ds_read_b128 v[2:5], v1 offset:11264
	ds_read_b128 v[6:9], v1 offset:27648
	global_store_dwordx2 v[16:17], v[18:19], off offset:1024 nt
	s_waitcnt lgkmcnt(0)
	v_pk_fma_f32 v[4:5], v[68:69], v[4:5], v[8:9]
	v_pk_fma_f32 v[2:3], v[66:67], v[2:3], v[6:7]
	v_cvt_pk_f16_f32 v7, v4, v5
	v_cvt_pk_f16_f32 v6, v2, v3
	global_store_dwordx2 v[14:15], v[6:7], off offset:1536 nt
	v_cvt_pk_bf16_f32 v2, v2, v3
	v_cvt_pk_bf16_f32 v3, v4, v5
	global_store_dwordx2 v[16:17], v[2:3], off offset:1536 nt
	ds_read_b128 v[2:5], v1 offset:12288
	ds_read_b128 v[6:9], v1 offset:28672
	s_waitcnt lgkmcnt(0)
	v_pk_fma_f32 v[4:5], v[72:73], v[4:5], v[8:9]
	v_pk_fma_f32 v[2:3], v[70:71], v[2:3], v[6:7]
	v_cvt_pk_f16_f32 v7, v4, v5
	v_cvt_pk_f16_f32 v6, v2, v3
	global_store_dwordx2 v[14:15], v[6:7], off offset:2048 nt
	v_cvt_pk_bf16_f32 v18, v2, v3
	v_cvt_pk_bf16_f32 v19, v4, v5
	ds_read_b128 v[2:5], v1 offset:13312
	ds_read_b128 v[6:9], v1 offset:29696
	global_store_dwordx2 v[16:17], v[18:19], off offset:2048 nt
	s_waitcnt lgkmcnt(0)
	v_pk_fma_f32 v[4:5], v[76:77], v[4:5], v[8:9]
	v_pk_fma_f32 v[2:3], v[74:75], v[2:3], v[6:7]
	v_cvt_pk_f16_f32 v7, v4, v5
	v_cvt_pk_f16_f32 v6, v2, v3
	global_store_dwordx2 v[14:15], v[6:7], off offset:2560 nt
	v_cvt_pk_bf16_f32 v18, v2, v3
	v_cvt_pk_bf16_f32 v19, v4, v5
	ds_read_b128 v[2:5], v1 offset:14336
	ds_read_b128 v[6:9], v1 offset:30720
	global_store_dwordx2 v[16:17], v[18:19], off offset:2560 nt
	s_waitcnt lgkmcnt(0)
	v_pk_fma_f32 v[4:5], v[80:81], v[4:5], v[8:9]
	v_pk_fma_f32 v[2:3], v[78:79], v[2:3], v[6:7]
	v_cvt_pk_f16_f32 v7, v4, v5
	v_cvt_pk_f16_f32 v6, v2, v3
	global_store_dwordx2 v[14:15], v[6:7], off offset:3072 nt
	v_cvt_pk_bf16_f32 v18, v2, v3
	v_cvt_pk_bf16_f32 v19, v4, v5
	ds_read_b128 v[2:5], v1 offset:15360
	ds_read_b128 v[6:9], v1 offset:31744
	global_store_dwordx2 v[16:17], v[18:19], off offset:3072 nt
	s_waitcnt lgkmcnt(0)
	v_pk_fma_f32 v[4:5], v[84:85], v[4:5], v[8:9]
	v_pk_fma_f32 v[2:3], v[82:83], v[2:3], v[6:7]
	v_cvt_pk_f16_f32 v7, v4, v5
	v_cvt_pk_f16_f32 v6, v2, v3
	global_store_dwordx2 v[14:15], v[6:7], off offset:3584 nt
	v_cvt_pk_bf16_f32 v2, v2, v3
	v_cvt_pk_bf16_f32 v3, v4, v5
	global_store_dwordx2 v[16:17], v[2:3], off offset:3584 nt
	s_cbranch_scc1 .LBB0_1101

.LBB0_1395:
	v_cmp_lt_i32_e32 vcc, v108, v107
	s_add_u32 s4, s6, s12
	s_addc_u32 s5, s7, s13
	v_cndmask_b32_e32 v4, v106, v108, vcc
	v_cmp_lt_i32_e32 vcc, v109, v107
	v_lshlrev_b32_e32 v133, 2, v4
	v_lshl_add_u64 v[2:3], v[36:37], 0, s[12:13]
	v_cndmask_b32_e32 v5, v106, v109, vcc
	v_cmp_lt_i32_e32 vcc, v110, v107
	v_lshlrev_b32_e32 v177, 2, v5
	v_lshl_add_u64 v[4:5], s[4:5], 0, v[34:35]
	v_cndmask_b32_e32 v6, v106, v110, vcc
	v_cmp_lt_i32_e32 vcc, v111, v107
	v_lshlrev_b32_e32 v180, 2, v6
	v_lshl_add_u64 v[40:41], v[4:5], 0, s[36:37]
	v_cndmask_b32_e32 v7, v106, v111, vcc
	v_cmp_lt_i32_e32 vcc, v112, v107
	v_lshlrev_b32_e32 v181, 2, v7
	v_lshl_add_u64 v[6:7], v[4:5], 0, s[34:35]
	v_cndmask_b32_e32 v8, v106, v112, vcc
	v_cmp_lt_i32_e32 vcc, v113, v107
	v_lshlrev_b32_e32 v182, 2, v8
	v_add_co_u32_e64 v38, s[4:5], s24, v4
	v_cndmask_b32_e32 v9, v106, v113, vcc
	v_add_co_u32_e32 v8, vcc, 0x2b200000, v4
	v_lshlrev_b32_e32 v183, 2, v9
	s_nop 0
	v_addc_co_u32_e32 v9, vcc, 0, v5, vcc
	global_load_dwordx2 v[42:43], v[6:7], off offset:512
	global_load_dwordx2 v[44:45], v[6:7], off offset:1024
	global_load_dwordx2 v[46:47], v[6:7], off offset:1536
	global_load_dwordx2 v[48:49], v[6:7], off offset:2048
	global_load_dwordx2 v[50:51], v[6:7], off offset:2560
	global_load_dwordx2 v[52:53], v[6:7], off offset:3072
	v_add_co_u32_e32 v4, vcc, s3, v4
	global_load_dwordx2 v[54:55], v[8:9], off
	global_load_dwordx2 v[56:57], v[6:7], off offset:3584
	v_addc_co_u32_e64 v39, s[4:5], 0, v5, s[4:5]
	v_addc_co_u32_e32 v5, vcc, 0, v5, vcc
	global_load_dwordx2 v[58:59], v[4:5], off
	global_load_dwordx2 v[60:61], v[4:5], off offset:512
	global_load_dwordx2 v[62:63], v[4:5], off offset:1024
	global_load_dwordx2 v[64:65], v[4:5], off offset:1536
	global_load_dwordx2 v[66:67], v[4:5], off offset:2048
	global_load_dwordx2 v[68:69], v[4:5], off offset:2560
	global_load_dwordx2 v[70:71], v[4:5], off offset:3072
	global_load_dwordx2 v[72:73], v[4:5], off offset:3584
	v_add_co_u32_e32 v6, vcc, s9, v2
	v_mov_b32_e32 v117, 0
	s_nop 0
	v_addc_co_u32_e32 v7, vcc, 0, v3, vcc
	v_add_co_u32_e32 v2, vcc, s11, v2
	v_mov_b32_e32 v118, 0
	s_nop 0
	v_addc_co_u32_e32 v3, vcc, 0, v3, vcc
	global_load_dwordx2 v[74:75], v[6:7], off offset:512
	global_load_dwordx2 v[76:77], v[6:7], off offset:1024
	global_load_dwordx2 v[78:79], v[6:7], off offset:1536
	global_load_dwordx2 v[80:81], v[6:7], off offset:2048
	global_load_dwordx2 v[82:83], v[6:7], off offset:2560
	global_load_dwordx2 v[84:85], v[6:7], off offset:3072
	global_load_dwordx2 v[86:87], v[2:3], off offset:-4096
	global_load_dwordx2 v[88:89], v[6:7], off offset:3584
	global_load_dwordx2 v[90:91], v[2:3], off
	global_load_dwordx2 v[92:93], v[2:3], off offset:512
	global_load_dwordx2 v[94:95], v[2:3], off offset:1024
	global_load_dwordx2 v[96:97], v[2:3], off offset:1536
	global_load_dwordx2 v[98:99], v[2:3], off offset:2048
	global_load_dwordx2 v[100:101], v[2:3], off offset:2560
	global_load_dwordx2 v[102:103], v[2:3], off offset:3072
	global_load_dwordx2 v[104:105], v[2:3], off offset:3584
	ds_read_b128 v[10:13], v1
	ds_read_b128 v[2:5], v1 offset:1024
	ds_read_b128 v[26:29], v1 offset:16384
	ds_read_b128 v[18:21], v1 offset:17408
	ds_read_b128 v[14:17], v1 offset:2048
	ds_read_b128 v[6:9], v1 offset:3072
	ds_read_b128 v[30:33], v1 offset:18432
	ds_read_b128 v[22:25], v1 offset:19456
	v_mov_b32_e32 v119, 0
	v_mov_b32_e32 v121, 0
	v_mov_b32_e32 v120, 0
	v_mov_b32_e32 v122, 0
	v_mov_b32_e32 v123, 0
	v_mov_b32_e32 v125, 0
	v_mov_b32_e32 v124, 0
	v_mov_b32_e32 v126, 0
	v_mov_b32_e32 v127, 0
	v_mov_b32_e32 v129, 0
	v_mov_b32_e32 v128, 0
	v_mov_b32_e32 v130, 0
	v_mov_b32_e32 v131, 0
	v_mov_b32_e32 v132, 0
	s_add_i32 s8, s8, s10
	v_lshl_add_u64 v[36:37], v[36:37], 0, s[14:15]
	s_waitcnt vmcnt(31)
	v_lshlrev_b32_e32 v134, 16, v42
	v_and_b32_e32 v135, 0xffff0000, v42
	v_lshlrev_b32_e32 v136, 16, v43
	v_and_b32_e32 v137, 0xffff0000, v43
	s_waitcnt vmcnt(28)
	v_lshlrev_b32_e32 v146, 16, v48
	v_and_b32_e32 v147, 0xffff0000, v48
	v_lshlrev_b32_e32 v138, 16, v44
	s_waitcnt vmcnt(25)
	v_lshlrev_b32_e32 v158, 16, v54
	v_and_b32_e32 v159, 0xffff0000, v54
	v_lshlrev_b32_e32 v160, 16, v55
	v_and_b32_e32 v161, 0xffff0000, v55
	s_waitcnt vmcnt(19)
	v_lshlrev_b32_e32 v187, 16, v66
	v_and_b32_e32 v188, 0xffff0000, v66
	v_lshlrev_b32_e32 v189, 16, v67
	v_and_b32_e32 v190, 0xffff0000, v67
	s_waitcnt vmcnt(18)
	v_lshlrev_b32_e32 v191, 16, v68
	v_and_b32_e32 v192, 0xffff0000, v68
	v_lshlrev_b32_e32 v193, 16, v69
	v_and_b32_e32 v194, 0xffff0000, v69
	s_waitcnt vmcnt(9)
	v_fma_mix_f32 v66, v86, s18, v158 op_sel_hi:[1,0,0]
	v_fma_mix_f32 v67, v86, s18, v159 op_sel:[1,0,0] op_sel_hi:[1,0,0]
	v_fma_mix_f32 v68, v87, s18, v160 op_sel_hi:[1,0,0]
	v_fma_mix_f32 v69, v87, s18, v161 op_sel:[1,0,0] op_sel_hi:[1,0,0]
	v_and_b32_e32 v139, 0xffff0000, v44
	v_lshlrev_b32_e32 v140, 16, v45
	v_and_b32_e32 v141, 0xffff0000, v45
	v_fma_mix_f32 v42, v74, s18, v134 op_sel_hi:[1,0,0]
	v_fma_mix_f32 v43, v74, s18, v135 op_sel:[1,0,0] op_sel_hi:[1,0,0]
	v_fma_mix_f32 v44, v75, s18, v136 op_sel_hi:[1,0,0]
	v_fma_mix_f32 v45, v75, s18, v137 op_sel:[1,0,0] op_sel_hi:[1,0,0]
	v_fma_mix_f32 v54, v80, s18, v146 op_sel_hi:[1,0,0]
	v_fma_mix_f32 v55, v80, s18, v147 op_sel:[1,0,0] op_sel_hi:[1,0,0]
	v_add_f32_e32 v146, v66, v67
	v_add_f32_e32 v147, v68, v69
	v_lshlrev_b32_e32 v142, 16, v46
	v_and_b32_e32 v143, 0xffff0000, v46
	v_lshlrev_b32_e32 v144, 16, v47
	v_and_b32_e32 v145, 0xffff0000, v47
	v_lshlrev_b32_e32 v148, 16, v49
	v_and_b32_e32 v149, 0xffff0000, v49
	v_fma_mix_f32 v46, v76, s18, v138 op_sel_hi:[1,0,0]
	v_fma_mix_f32 v47, v76, s18, v139 op_sel:[1,0,0] op_sel_hi:[1,0,0]
	v_fma_mix_f32 v48, v77, s18, v140 op_sel_hi:[1,0,0]
	v_fma_mix_f32 v49, v77, s18, v141 op_sel:[1,0,0] op_sel_hi:[1,0,0]
	v_add_f32_e32 v134, v42, v43
	v_add_f32_e32 v135, v44, v45
	v_add_f32_e32 v146, v146, v147
	v_lshlrev_b32_e32 v150, 16, v50
	v_and_b32_e32 v151, 0xffff0000, v50
	v_lshlrev_b32_e32 v152, 16, v51
	v_and_b32_e32 v153, 0xffff0000, v51
	v_lshlrev_b32_e32 v154, 16, v52
	v_and_b32_e32 v155, 0xffff0000, v52
	v_lshlrev_b32_e32 v156, 16, v53
	v_and_b32_e32 v157, 0xffff0000, v53
	v_fma_mix_f32 v50, v78, s18, v142 op_sel_hi:[1,0,0]
	v_fma_mix_f32 v51, v78, s18, v143 op_sel:[1,0,0] op_sel_hi:[1,0,0]
	v_fma_mix_f32 v52, v79, s18, v144 op_sel_hi:[1,0,0]
	v_fma_mix_f32 v53, v79, s18, v145 op_sel:[1,0,0] op_sel_hi:[1,0,0]
	v_add_f32_e32 v136, v46, v47
	v_add_f32_e32 v137, v48, v49
	v_add_f32_e32 v134, v134, v135
	v_add_f32_e32 v146, 0, v146
	v_lshlrev_b32_e32 v162, 16, v56
	v_and_b32_e32 v163, 0xffff0000, v56
	v_lshlrev_b32_e32 v164, 16, v57
	v_and_b32_e32 v165, 0xffff0000, v57
	v_fma_mix_f32 v56, v81, s18, v148 op_sel_hi:[1,0,0]
	v_fma_mix_f32 v57, v81, s18, v149 op_sel:[1,0,0] op_sel_hi:[1,0,0]
	v_add_f32_e32 v138, v50, v51
	v_add_f32_e32 v139, v52, v53
	v_add_f32_e32 v135, v136, v137
	v_add_f32_e32 v134, v146, v134
	v_lshlrev_b32_e32 v166, 16, v58
	v_and_b32_e32 v167, 0xffff0000, v58
	v_lshlrev_b32_e32 v168, 16, v59
	v_and_b32_e32 v169, 0xffff0000, v59
	v_lshlrev_b32_e32 v170, 16, v60
	v_and_b32_e32 v171, 0xffff0000, v60
	v_lshlrev_b32_e32 v172, 16, v61
	v_and_b32_e32 v173, 0xffff0000, v61
	v_fma_mix_f32 v58, v82, s18, v150 op_sel_hi:[1,0,0]
	v_fma_mix_f32 v59, v82, s18, v151 op_sel:[1,0,0] op_sel_hi:[1,0,0]
	v_fma_mix_f32 v60, v83, s18, v152 op_sel_hi:[1,0,0]
	v_fma_mix_f32 v61, v83, s18, v153 op_sel:[1,0,0] op_sel_hi:[1,0,0]
	v_add_f32_e32 v140, v54, v55
	v_add_f32_e32 v141, v56, v57
	v_add_f32_e32 v136, v138, v139
	v_add_f32_e32 v134, v134, v135
	v_lshlrev_b32_e32 v174, 16, v62
	v_and_b32_e32 v175, 0xffff0000, v62
	v_lshlrev_b32_e32 v176, 16, v63
	v_and_b32_e32 v178, 0xffff0000, v63
	v_lshlrev_b32_e32 v179, 16, v64
	v_and_b32_e32 v184, 0xffff0000, v64
	v_lshlrev_b32_e32 v185, 16, v65
	v_and_b32_e32 v186, 0xffff0000, v65
	v_fma_mix_f32 v62, v84, s18, v154 op_sel_hi:[1,0,0]
	v_fma_mix_f32 v63, v84, s18, v155 op_sel:[1,0,0] op_sel_hi:[1,0,0]
	v_fma_mix_f32 v64, v85, s18, v156 op_sel_hi:[1,0,0]
	v_fma_mix_f32 v65, v85, s18, v157 op_sel:[1,0,0] op_sel_hi:[1,0,0]
	v_add_f32_e32 v142, v58, v59
	v_add_f32_e32 v143, v60, v61
	v_add_f32_e32 v137, v140, v141
	v_add_f32_e32 v134, v134, v136
	v_lshlrev_b32_e32 v195, 16, v70
	v_and_b32_e32 v196, 0xffff0000, v70
	v_lshlrev_b32_e32 v197, 16, v71
	v_and_b32_e32 v198, 0xffff0000, v71
	v_lshlrev_b32_e32 v199, 16, v72
	v_and_b32_e32 v200, 0xffff0000, v72
	v_lshlrev_b32_e32 v201, 16, v73
	v_and_b32_e32 v202, 0xffff0000, v73
	v_add_f32_e32 v144, v62, v63
	v_add_f32_e32 v145, v64, v65
	s_waitcnt vmcnt(8)
	v_fma_mix_f32 v70, v88, s18, v162 op_sel_hi:[1,0,0]
	v_fma_mix_f32 v71, v88, s18, v163 op_sel:[1,0,0] op_sel_hi:[1,0,0]
	v_fma_mix_f32 v72, v89, s18, v164 op_sel_hi:[1,0,0]
	v_fma_mix_f32 v73, v89, s18, v165 op_sel:[1,0,0] op_sel_hi:[1,0,0]
	v_add_f32_e32 v138, v142, v143
	v_add_f32_e32 v134, v134, v137
	s_waitcnt vmcnt(7)
	v_fma_mix_f32 v74, v90, s18, v166 op_sel_hi:[1,0,0]
	v_fma_mix_f32 v75, v90, s18, v167 op_sel:[1,0,0] op_sel_hi:[1,0,0]
	v_fma_mix_f32 v76, v91, s18, v168 op_sel_hi:[1,0,0]
	v_fma_mix_f32 v77, v91, s18, v169 op_sel:[1,0,0] op_sel_hi:[1,0,0]
	v_add_f32_e32 v139, v144, v145
	v_add_f32_e32 v140, v70, v71
	v_add_f32_e32 v141, v72, v73
	v_add_f32_e32 v134, v134, v138
	s_waitcnt vmcnt(6)
	v_fma_mix_f32 v78, v92, s18, v170 op_sel_hi:[1,0,0]
	v_fma_mix_f32 v79, v92, s18, v171 op_sel:[1,0,0] op_sel_hi:[1,0,0]
	v_fma_mix_f32 v80, v93, s18, v172 op_sel_hi:[1,0,0]
	v_fma_mix_f32 v81, v93, s18, v173 op_sel:[1,0,0] op_sel_hi:[1,0,0]
	v_add_f32_e32 v142, v74, v75
	v_add_f32_e32 v143, v76, v77
	v_add_f32_e32 v140, v140, v141
	v_add_f32_e32 v134, v134, v139
	s_waitcnt vmcnt(5)
	v_fma_mix_f32 v82, v94, s18, v174 op_sel_hi:[1,0,0]
	v_fma_mix_f32 v83, v94, s18, v175 op_sel:[1,0,0] op_sel_hi:[1,0,0]
	v_fma_mix_f32 v84, v95, s18, v176 op_sel_hi:[1,0,0]
	v_fma_mix_f32 v85, v95, s18, v178 op_sel:[1,0,0] op_sel_hi:[1,0,0]
	v_add_f32_e32 v144, v78, v79
	v_add_f32_e32 v145, v80, v81
	v_add_f32_e32 v141, v142, v143
	v_add_f32_e32 v134, v134, v140
	s_waitcnt vmcnt(4)
	v_fma_mix_f32 v86, v96, s18, v179 op_sel_hi:[1,0,0]
	v_fma_mix_f32 v87, v96, s18, v184 op_sel:[1,0,0] op_sel_hi:[1,0,0]
	v_fma_mix_f32 v88, v97, s18, v185 op_sel_hi:[1,0,0]
	v_fma_mix_f32 v89, v97, s18, v186 op_sel:[1,0,0] op_sel_hi:[1,0,0]
	v_add_f32_e32 v148, v82, v83
	v_add_f32_e32 v149, v84, v85
	v_add_f32_e32 v142, v144, v145
	v_add_f32_e32 v134, v134, v141
	s_waitcnt vmcnt(3)
	v_fma_mix_f32 v90, v98, s18, v187 op_sel_hi:[1,0,0]
	v_fma_mix_f32 v91, v98, s18, v188 op_sel:[1,0,0] op_sel_hi:[1,0,0]
	v_fma_mix_f32 v92, v99, s18, v189 op_sel_hi:[1,0,0]
	v_fma_mix_f32 v93, v99, s18, v190 op_sel:[1,0,0] op_sel_hi:[1,0,0]
	v_add_f32_e32 v150, v86, v87
	v_add_f32_e32 v151, v88, v89
	v_add_f32_e32 v143, v148, v149
	v_add_f32_e32 v134, v134, v142
	s_waitcnt vmcnt(2)
	v_fma_mix_f32 v94, v100, s18, v191 op_sel_hi:[1,0,0]
	v_fma_mix_f32 v95, v100, s18, v192 op_sel:[1,0,0] op_sel_hi:[1,0,0]
	v_fma_mix_f32 v96, v101, s18, v193 op_sel_hi:[1,0,0]
	v_fma_mix_f32 v97, v101, s18, v194 op_sel:[1,0,0] op_sel_hi:[1,0,0]
	v_add_f32_e32 v152, v90, v91
	v_add_f32_e32 v153, v92, v93
	v_add_f32_e32 v144, v150, v151
	v_add_f32_e32 v134, v134, v143
	s_waitcnt vmcnt(1)
	v_fma_mix_f32 v98, v102, s18, v195 op_sel_hi:[1,0,0]
	v_fma_mix_f32 v99, v102, s18, v196 op_sel:[1,0,0] op_sel_hi:[1,0,0]
	v_fma_mix_f32 v100, v103, s18, v197 op_sel_hi:[1,0,0]
	v_fma_mix_f32 v101, v103, s18, v198 op_sel:[1,0,0] op_sel_hi:[1,0,0]
	v_add_f32_e32 v154, v94, v95
	v_add_f32_e32 v155, v96, v97
	v_add_f32_e32 v145, v152, v153
	v_add_f32_e32 v134, v134, v144
	s_waitcnt vmcnt(0)
	v_fma_mix_f32 v102, v104, s18, v199 op_sel_hi:[1,0,0]
	v_fma_mix_f32 v103, v104, s18, v200 op_sel:[1,0,0] op_sel_hi:[1,0,0]
	v_fma_mix_f32 v104, v105, s18, v201 op_sel_hi:[1,0,0]
	v_fma_mix_f32 v105, v105, s18, v202 op_sel:[1,0,0] op_sel_hi:[1,0,0]
	v_add_f32_e32 v156, v98, v99
	v_add_f32_e32 v157, v100, v101
	v_add_f32_e32 v147, v154, v155
	v_add_f32_e32 v134, v134, v145
	v_add_f32_e32 v158, v102, v103
	v_add_f32_e32 v159, v104, v105
	v_add_f32_e32 v148, v156, v157
	v_add_f32_e32 v134, v134, v147
	v_add_f32_e32 v149, v158, v159
	v_add_f32_e32 v134, v134, v148
	v_add_f32_e32 v134, v134, v149
	ds_bpermute_b32 v135, v133, v134
	s_waitcnt lgkmcnt(0)
	v_add_f32_e32 v134, v134, v135
	ds_bpermute_b32 v135, v177, v134
	s_waitcnt lgkmcnt(0)
	v_add_f32_e32 v134, v134, v135
	ds_bpermute_b32 v135, v180, v134
	s_waitcnt lgkmcnt(0)
	v_add_f32_e32 v134, v134, v135
	ds_bpermute_b32 v135, v181, v134
	s_waitcnt lgkmcnt(0)
	v_add_f32_e32 v134, v134, v135
	ds_bpermute_b32 v135, v182, v134
	s_waitcnt lgkmcnt(0)
	v_add_f32_e32 v134, v134, v135
	ds_bpermute_b32 v135, v183, v134
	s_waitcnt lgkmcnt(0)
	v_add_f32_e32 v134, v134, v135
	v_fmac_f32_e32 v67, 0xb9800000, v134
	v_fmac_f32_e32 v66, 0xb9800000, v134
	v_fmac_f32_e32 v69, 0xb9800000, v134
	v_fmac_f32_e32 v68, 0xb9800000, v134
	v_fmac_f32_e32 v43, 0xb9800000, v134
	v_fmac_f32_e32 v42, 0xb9800000, v134
	v_fmac_f32_e32 v45, 0xb9800000, v134
	v_fmac_f32_e32 v44, 0xb9800000, v134
	v_fmac_f32_e32 v47, 0xb9800000, v134
	v_fmac_f32_e32 v46, 0xb9800000, v134
	v_fmac_f32_e32 v49, 0xb9800000, v134
	v_fmac_f32_e32 v48, 0xb9800000, v134
	v_fmac_f32_e32 v53, 0xb9800000, v134
	v_fmac_f32_e32 v52, 0xb9800000, v134
	v_fmac_f32_e32 v51, 0xb9800000, v134
	v_fmac_f32_e32 v50, 0xb9800000, v134
	v_fmac_f32_e32 v55, 0xb9800000, v134
	v_fmac_f32_e32 v54, 0xb9800000, v134
	v_fmac_f32_e32 v57, 0xb9800000, v134
	v_fmac_f32_e32 v56, 0xb9800000, v134
	v_fmac_f32_e32 v59, 0xb9800000, v134
	v_fmac_f32_e32 v58, 0xb9800000, v134
	v_fmac_f32_e32 v61, 0xb9800000, v134
	v_fmac_f32_e32 v60, 0xb9800000, v134
	v_fmac_f32_e32 v65, 0xb9800000, v134
	v_fmac_f32_e32 v64, 0xb9800000, v134
	v_fmac_f32_e32 v63, 0xb9800000, v134
	v_fmac_f32_e32 v62, 0xb9800000, v134
	v_fmac_f32_e32 v71, 0xb9800000, v134
	v_fmac_f32_e32 v70, 0xb9800000, v134
	v_fmac_f32_e32 v73, 0xb9800000, v134
	v_fmac_f32_e32 v72, 0xb9800000, v134
	v_fmac_f32_e32 v75, 0xb9800000, v134
	v_fmac_f32_e32 v74, 0xb9800000, v134
	v_fmac_f32_e32 v77, 0xb9800000, v134
	v_fmac_f32_e32 v76, 0xb9800000, v134
	v_fmac_f32_e32 v81, 0xb9800000, v134
	v_fmac_f32_e32 v80, 0xb9800000, v134
	v_fmac_f32_e32 v79, 0xb9800000, v134
	v_fmac_f32_e32 v78, 0xb9800000, v134
	v_fmac_f32_e32 v83, 0xb9800000, v134
	v_fmac_f32_e32 v82, 0xb9800000, v134
	v_fmac_f32_e32 v85, 0xb9800000, v134
	v_fmac_f32_e32 v84, 0xb9800000, v134
	v_fmac_f32_e32 v87, 0xb9800000, v134
	v_fmac_f32_e32 v86, 0xb9800000, v134
	v_fmac_f32_e32 v89, 0xb9800000, v134
	v_fmac_f32_e32 v88, 0xb9800000, v134
	v_fmac_f32_e32 v93, 0xb9800000, v134
	v_fmac_f32_e32 v92, 0xb9800000, v134
	v_fmac_f32_e32 v91, 0xb9800000, v134
	v_fmac_f32_e32 v90, 0xb9800000, v134
	v_fmac_f32_e32 v95, 0xb9800000, v134
	v_fmac_f32_e32 v94, 0xb9800000, v134
	v_fmac_f32_e32 v97, 0xb9800000, v134
	v_fmac_f32_e32 v96, 0xb9800000, v134
	v_fmac_f32_e32 v99, 0xb9800000, v134
	v_fmac_f32_e32 v98, 0xb9800000, v134
	v_fmac_f32_e32 v101, 0xb9800000, v134
	v_fmac_f32_e32 v100, 0xb9800000, v134
	v_fmac_f32_e32 v105, 0xb9800000, v134
	v_fmac_f32_e32 v104, 0xb9800000, v134
	v_fmac_f32_e32 v103, 0xb9800000, v134
	v_fmac_f32_e32 v102, 0xb9800000, v134
	v_pk_mul_f32 v[134:135], v[68:69], v[68:69]
	v_pk_mul_f32 v[136:137], v[66:67], v[66:67]
	v_pk_mul_f32 v[138:139], v[44:45], v[44:45]
	v_pk_mul_f32 v[140:141], v[42:43], v[42:43]
	v_pk_mov_b32 v[178:179], v[136:137], v[134:135] op_sel:[1,0]
	v_mov_b32_e32 v137, v135
	v_pk_mov_b32 v[134:135], v[140:141], v[138:139] op_sel:[1,0]
	v_mov_b32_e32 v141, v139
	v_mul_f32_e32 v142, v46, v46
	v_mul_f32_e32 v144, v48, v48
	v_pk_add_f32 v[136:137], v[178:179], v[136:137]
	v_pk_add_f32 v[134:135], v[134:135], v[140:141]
	v_pk_fma_f32 v[138:139], v[46:47], v[46:47], v[142:143] op_sel_hi:[1,1,0]
	v_pk_fma_f32 v[142:143], v[48:49], v[48:49], v[144:145] op_sel_hi:[1,1,0]
	v_pk_add_f32 v[136:137], v[136:137], v[136:137] op_sel_hi:[0,1]
	v_pk_add_f32 v[134:135], v[134:135], v[134:135] op_sel_hi:[0,1]
	v_pk_mul_f32 v[146:147], v[56:57], v[56:57]
	v_pk_mul_f32 v[148:149], v[54:55], v[54:55]
	v_mul_f32_e32 v138, v50, v50
	v_mul_f32_e32 v142, v51, v51
	v_mul_f32_e32 v136, v52, v52
	v_mul_f32_e32 v134, v53, v53
	v_pk_mov_b32 v[144:145], v[148:149], v[146:147] op_sel:[1,0]
	v_mov_b32_e32 v149, v147
	v_pk_add_f32 v[138:139], v[138:139], v[142:143]
	v_pk_add_f32 v[134:135], v[136:137], v[134:135]
	v_mul_f32_e32 v150, v58, v58
	v_mul_f32_e32 v152, v60, v60
	v_pk_add_f32 v[140:141], v[144:145], v[148:149]
	v_pk_add_f32 v[134:135], v[138:139], v[134:135]
	v_pk_fma_f32 v[146:147], v[58:59], v[58:59], v[150:151] op_sel_hi:[1,1,0]
	v_pk_fma_f32 v[150:151], v[60:61], v[60:61], v[152:153] op_sel_hi:[1,1,0]
	v_pk_add_f32 v[140:141], v[140:141], v[140:141] op_sel_hi:[0,1]
	v_pk_add_f32 v[134:135], v[134:135], v[134:135] op_sel_hi:[0,1]
	v_pk_mul_f32 v[154:155], v[72:73], v[72:73]
	v_pk_mul_f32 v[156:157], v[70:71], v[70:71]
	v_mul_f32_e32 v146, v62, v62
	v_mul_f32_e32 v150, v63, v63
	v_mul_f32_e32 v140, v64, v64
	v_mul_f32_e32 v134, v65, v65
	v_pk_mov_b32 v[152:153], v[156:157], v[154:155] op_sel:[1,0]
	v_mov_b32_e32 v157, v155
	v_pk_add_f32 v[142:143], v[146:147], v[150:151]
	v_pk_add_f32 v[134:135], v[140:141], v[134:135]
	v_mul_f32_e32 v158, v74, v74
	v_mul_f32_e32 v160, v76, v76
	v_pk_add_f32 v[144:145], v[152:153], v[156:157]
	v_pk_add_f32 v[134:135], v[142:143], v[134:135]
	v_pk_fma_f32 v[154:155], v[74:75], v[74:75], v[158:159] op_sel_hi:[1,1,0]
	v_pk_fma_f32 v[158:159], v[76:77], v[76:77], v[160:161] op_sel_hi:[1,1,0]
	v_pk_add_f32 v[144:145], v[144:145], v[144:145] op_sel_hi:[0,1]
	v_pk_add_f32 v[134:135], v[134:135], v[134:135] op_sel_hi:[0,1]
	v_pk_mul_f32 v[162:163], v[84:85], v[84:85]
	v_pk_mul_f32 v[164:165], v[82:83], v[82:83]
	v_mul_f32_e32 v154, v78, v78
	v_mul_f32_e32 v158, v79, v79
	v_mul_f32_e32 v144, v80, v80
	v_mul_f32_e32 v134, v81, v81
	v_pk_mov_b32 v[160:161], v[164:165], v[162:163] op_sel:[1,0]
	v_mov_b32_e32 v165, v163
	v_pk_add_f32 v[146:147], v[154:155], v[158:159]
	v_pk_add_f32 v[134:135], v[144:145], v[134:135]
	v_mul_f32_e32 v166, v86, v86
	v_mul_f32_e32 v168, v88, v88
	v_pk_add_f32 v[148:149], v[160:161], v[164:165]
	v_pk_add_f32 v[134:135], v[146:147], v[134:135]
	v_pk_fma_f32 v[162:163], v[86:87], v[86:87], v[166:167] op_sel_hi:[1,1,0]
	v_pk_fma_f32 v[166:167], v[88:89], v[88:89], v[168:169] op_sel_hi:[1,1,0]
	v_pk_add_f32 v[148:149], v[148:149], v[148:149] op_sel_hi:[0,1]
	v_pk_add_f32 v[134:135], v[134:135], v[134:135] op_sel_hi:[0,1]
	v_pk_mul_f32 v[170:171], v[96:97], v[96:97]
	v_pk_mul_f32 v[172:173], v[94:95], v[94:95]
	v_mul_f32_e32 v162, v90, v90
	v_mul_f32_e32 v166, v91, v91
	v_mul_f32_e32 v148, v92, v92
	v_mul_f32_e32 v134, v93, v93
	v_pk_mov_b32 v[168:169], v[172:173], v[170:171] op_sel:[1,0]
	v_mov_b32_e32 v173, v171
	v_pk_add_f32 v[150:151], v[162:163], v[166:167]
	v_pk_add_f32 v[134:135], v[148:149], v[134:135]
	v_mul_f32_e32 v174, v98, v98
	v_mul_f32_e32 v176, v100, v100
	v_pk_add_f32 v[152:153], v[168:169], v[172:173]
	v_pk_add_f32 v[134:135], v[150:151], v[134:135]
	v_pk_fma_f32 v[170:171], v[98:99], v[98:99], v[174:175] op_sel_hi:[1,1,0]
	v_pk_fma_f32 v[174:175], v[100:101], v[100:101], v[176:177] op_sel_hi:[1,1,0]
	v_pk_add_f32 v[152:153], v[152:153], v[152:153] op_sel_hi:[0,1]
	v_pk_add_f32 v[134:135], v[134:135], v[134:135] op_sel_hi:[0,1]
	v_mul_f32_e32 v170, v102, v102
	v_mul_f32_e32 v174, v103, v103
	v_mul_f32_e32 v152, v104, v104
	v_mul_f32_e32 v134, v105, v105
	v_pk_add_f32 v[154:155], v[170:171], v[174:175]
	v_pk_add_f32 v[134:135], v[152:153], v[134:135]
	s_nop 0
	v_pk_add_f32 v[134:135], v[154:155], v[134:135]
	s_nop 0
	v_add_f32_e32 v134, v134, v135
	ds_bpermute_b32 v133, v133, v134
	s_waitcnt lgkmcnt(0)
	v_add_f32_e32 v133, v134, v133
	ds_bpermute_b32 v134, v177, v133
	s_waitcnt lgkmcnt(0)
	v_add_f32_e32 v133, v133, v134
	ds_bpermute_b32 v134, v180, v133
	s_waitcnt lgkmcnt(0)
	v_add_f32_e32 v133, v133, v134
	ds_bpermute_b32 v134, v181, v133
	s_waitcnt lgkmcnt(0)
	v_add_f32_e32 v133, v133, v134
	ds_bpermute_b32 v134, v182, v133
	s_waitcnt lgkmcnt(0)
	v_add_f32_e32 v133, v133, v134
	ds_bpermute_b32 v134, v183, v133
	s_waitcnt lgkmcnt(0)
	v_add_f32_e32 v133, v133, v134
	v_fmamk_f32 v133, v133, 0x39800000, v114
	v_mul_f32_e32 v134, 0x4f800000, v133
	v_cmp_gt_f32_e32 vcc, s19, v133
	s_nop 1
	v_cndmask_b32_e32 v133, v133, v134, vcc
	v_sqrt_f32_e32 v134, v133
	s_nop 0
	v_add_u32_e32 v135, -1, v134
	v_add_u32_e32 v136, 1, v134
	v_fma_f32 v137, -v135, v134, v133
	v_fma_f32 v138, -v136, v134, v133
	v_cmp_ge_f32_e64 s[4:5], 0, v137
	s_nop 1
	v_cndmask_b32_e64 v134, v134, v135, s[4:5]
	v_cmp_lt_f32_e64 s[4:5], 0, v138
	s_nop 1
	v_cndmask_b32_e64 v134, v134, v136, s[4:5]
	v_mul_f32_e32 v135, 0x37800000, v134
	v_cndmask_b32_e32 v134, v134, v135, vcc
	v_cmp_class_f32_e32 vcc, v133, v115
	s_nop 1
	v_cndmask_b32_e32 v133, v134, v133, vcc
	v_div_scale_f32 v134, s[4:5], v133, v133, 1.0
	v_rcp_f32_e32 v136, v134
	v_div_scale_f32 v135, vcc, 1.0, v133, 1.0
	v_fma_f32 v137, -v134, v136, 1.0
	v_fmac_f32_e32 v136, v137, v136
	v_mul_f32_e32 v137, v135, v136
	v_fma_f32 v138, -v134, v137, v135
	v_fmac_f32_e32 v137, v138, v136
	v_fma_f32 v134, -v134, v137, v135
	v_div_fmas_f32 v134, v134, v136, v137
	v_div_fixup_f32 v134, v134, v133, 1.0
	v_pk_mul_f32 v[66:67], v[66:67], v[134:135] op_sel_hi:[1,0]
	v_pk_mul_f32 v[42:43], v[42:43], v[134:135] op_sel_hi:[1,0]
	v_pk_fma_f32 v[10:11], v[10:11], v[66:67], v[26:27]
	v_pk_fma_f32 v[2:3], v[2:3], v[42:43], v[18:19]
	v_cvt_pk_fp8_f32 v117, v10, v11
	v_pk_mul_f32 v[68:69], v[68:69], v[134:135] op_sel_hi:[1,0]
	v_pk_mul_f32 v[46:47], v[46:47], v[134:135] op_sel_hi:[1,0]
	v_pk_mul_f32 v[50:51], v[50:51], v[134:135] op_sel_hi:[1,0]
	v_cvt_pk_fp8_f32 v118, v2, v3
	v_pk_fma_f32 v[12:13], v[12:13], v[68:69], v[28:29]
	v_pk_fma_f32 v[14:15], v[14:15], v[46:47], v[30:31]
	v_pk_fma_f32 v[6:7], v[6:7], v[50:51], v[22:23]
	v_pk_mul_f32 v[44:45], v[44:45], v[134:135] op_sel_hi:[1,0]
	v_cvt_pk_fp8_f32 v119, v14, v15
	v_cvt_pk_fp8_f32 v121, v6, v7
	v_cvt_pk_fp8_f32 v117, v12, v13 op_sel:[0,0,1]
	v_pk_fma_f32 v[4:5], v[4:5], v[44:45], v[20:21]
	v_pk_mul_f32 v[48:49], v[48:49], v[134:135] op_sel_hi:[1,0]
	v_pk_mul_f32 v[52:53], v[52:53], v[134:135] op_sel_hi:[1,0]
	v_cvt_pk_fp8_f32 v118, v4, v5 op_sel:[0,0,1]
	v_pk_fma_f32 v[16:17], v[16:17], v[48:49], v[32:33]
	v_pk_fma_f32 v[8:9], v[8:9], v[52:53], v[24:25]
	v_cvt_pk_f16_f32 v19, v12, v13
	v_cvt_pk_f16_f32 v18, v10, v11
	v_cvt_pk_f16_f32 v11, v4, v5
	v_cvt_pk_f16_f32 v10, v2, v3
	v_cvt_pk_f16_f32 v3, v16, v17
	v_cvt_pk_f16_f32 v2, v14, v15
	v_cvt_pk_f16_f32 v15, v8, v9
	v_cvt_pk_f16_f32 v14, v6, v7
	global_store_dwordx2 v[38:39], v[18:19], off offset:-4096 nt
	v_cvt_pk_fp8_f32 v119, v16, v17 op_sel:[0,0,1]
	v_cvt_pk_fp8_f32 v121, v8, v9 op_sel:[0,0,1]
	global_store_dword v116, v117, s[16:17] nt
	global_store_dwordx2 v[40:41], v[10:11], off offset:512 nt
	global_store_dword v116, v118, s[16:17] offset:256 nt
	global_store_dwordx2 v[40:41], v[2:3], off offset:1024 nt
	global_store_dword v116, v119, s[16:17] offset:512 nt
	global_store_dwordx2 v[40:41], v[14:15], off offset:1536 nt
	global_store_dword v116, v121, s[16:17] offset:768 nt
	v_pk_mul_f32 v[54:55], v[54:55], v[134:135] op_sel_hi:[1,0]
	ds_read_b128 v[2:5], v1 offset:4096
	ds_read_b128 v[6:9], v1 offset:5120
	ds_read_b128 v[10:13], v1 offset:20480
	ds_read_b128 v[14:17], v1 offset:21504
	ds_read_b128 v[18:21], v1 offset:6144
	ds_read_b128 v[22:25], v1 offset:7168
	ds_read_b128 v[26:29], v1 offset:22528
	ds_read_b128 v[30:33], v1 offset:23552
	s_waitcnt lgkmcnt(5)
	v_pk_fma_f32 v[2:3], v[2:3], v[54:55], v[10:11]
	v_pk_mul_f32 v[58:59], v[58:59], v[134:135] op_sel_hi:[1,0]
	v_cvt_pk_fp8_f32 v120, v2, v3
	s_waitcnt lgkmcnt(4)
	v_pk_fma_f32 v[6:7], v[6:7], v[58:59], v[14:15]
	v_pk_mul_f32 v[56:57], v[56:57], v[134:135] op_sel_hi:[1,0]
	v_pk_mul_f32 v[60:61], v[60:61], v[134:135] op_sel_hi:[1,0]
	v_pk_mul_f32 v[62:63], v[62:63], v[134:135] op_sel_hi:[1,0]
	v_pk_mul_f32 v[70:71], v[70:71], v[134:135] op_sel_hi:[1,0]
	v_cvt_pk_fp8_f32 v122, v6, v7
	v_pk_fma_f32 v[4:5], v[4:5], v[56:57], v[12:13]
	v_pk_fma_f32 v[8:9], v[8:9], v[60:61], v[16:17]
	s_waitcnt lgkmcnt(1)
	v_pk_fma_f32 v[12:13], v[62:63], v[18:19], v[26:27]
	s_waitcnt lgkmcnt(0)
	v_pk_fma_f32 v[16:17], v[70:71], v[22:23], v[30:31]
	v_cvt_pk_fp8_f32 v123, v12, v13
	v_cvt_pk_fp8_f32 v125, v16, v17
	v_cvt_pk_fp8_f32 v120, v4, v5 op_sel:[0,0,1]
	v_pk_mul_f32 v[64:65], v[64:65], v[134:135] op_sel_hi:[1,0]
	v_pk_mul_f32 v[72:73], v[72:73], v[134:135] op_sel_hi:[1,0]
	v_cvt_pk_fp8_f32 v122, v8, v9 op_sel:[0,0,1]
	v_pk_fma_f32 v[10:11], v[64:65], v[20:21], v[28:29]
	v_pk_fma_f32 v[14:15], v[72:73], v[24:25], v[32:33]
	v_cvt_pk_f16_f32 v18, v2, v3
	v_cvt_pk_f16_f32 v19, v4, v5
	v_cvt_pk_f16_f32 v2, v6, v7
	v_cvt_pk_f16_f32 v3, v8, v9
	v_cvt_pk_f16_f32 v6, v12, v13
	v_cvt_pk_f16_f32 v7, v10, v11
	v_cvt_pk_f16_f32 v12, v16, v17
	v_cvt_pk_f16_f32 v13, v14, v15
	global_store_dwordx2 v[40:41], v[18:19], off offset:2048 nt
	v_cvt_pk_fp8_f32 v123, v10, v11 op_sel:[0,0,1]
	v_cvt_pk_fp8_f32 v125, v14, v15 op_sel:[0,0,1]
	global_store_dword v116, v120, s[16:17] offset:1024 nt
	global_store_dwordx2 v[40:41], v[2:3], off offset:2560 nt
	global_store_dword v116, v122, s[16:17] offset:1280 nt
	global_store_dwordx2 v[40:41], v[6:7], off offset:3072 nt
	global_store_dword v116, v123, s[16:17] offset:1536 nt
	global_store_dwordx2 v[40:41], v[12:13], off offset:3584 nt
	global_store_dword v116, v125, s[16:17] offset:1792 nt
	v_pk_mul_f32 v[74:75], v[74:75], v[134:135] op_sel_hi:[1,0]
	ds_read_b128 v[2:5], v1 offset:8192
	ds_read_b128 v[6:9], v1 offset:9216
	ds_read_b128 v[10:13], v1 offset:24576
	ds_read_b128 v[14:17], v1 offset:25600
	ds_read_b128 v[18:21], v1 offset:10240
	ds_read_b128 v[22:25], v1 offset:11264
	ds_read_b128 v[26:29], v1 offset:26624
	ds_read_b128 v[30:33], v1 offset:27648
	s_waitcnt lgkmcnt(5)
	v_pk_fma_f32 v[2:3], v[74:75], v[2:3], v[10:11]
	v_pk_mul_f32 v[78:79], v[78:79], v[134:135] op_sel_hi:[1,0]
	v_cvt_pk_fp8_f32 v124, v2, v3
	s_waitcnt lgkmcnt(4)
	v_pk_fma_f32 v[6:7], v[78:79], v[6:7], v[14:15]
	v_pk_mul_f32 v[76:77], v[76:77], v[134:135] op_sel_hi:[1,0]
	v_pk_mul_f32 v[80:81], v[80:81], v[134:135] op_sel_hi:[1,0]
	v_pk_mul_f32 v[82:83], v[82:83], v[134:135] op_sel_hi:[1,0]
	v_pk_mul_f32 v[86:87], v[86:87], v[134:135] op_sel_hi:[1,0]
	v_cvt_pk_fp8_f32 v126, v6, v7
	v_pk_fma_f32 v[4:5], v[76:77], v[4:5], v[12:13]
	v_pk_fma_f32 v[8:9], v[80:81], v[8:9], v[16:17]
	s_waitcnt lgkmcnt(1)
	v_pk_fma_f32 v[12:13], v[82:83], v[18:19], v[26:27]
	s_waitcnt lgkmcnt(0)
	v_pk_fma_f32 v[16:17], v[86:87], v[22:23], v[30:31]
	v_cvt_pk_fp8_f32 v127, v12, v13
	v_cvt_pk_fp8_f32 v129, v16, v17
	v_cvt_pk_fp8_f32 v124, v4, v5 op_sel:[0,0,1]
	v_pk_mul_f32 v[84:85], v[84:85], v[134:135] op_sel_hi:[1,0]
	v_pk_mul_f32 v[88:89], v[88:89], v[134:135] op_sel_hi:[1,0]
	v_cvt_pk_fp8_f32 v126, v8, v9 op_sel:[0,0,1]
	v_pk_fma_f32 v[10:11], v[84:85], v[20:21], v[28:29]
	v_pk_fma_f32 v[14:15], v[88:89], v[24:25], v[32:33]
	v_cvt_pk_f16_f32 v18, v2, v3
	v_cvt_pk_f16_f32 v19, v4, v5
	v_cvt_pk_f16_f32 v2, v6, v7
	v_cvt_pk_f16_f32 v3, v8, v9
	v_cvt_pk_f16_f32 v6, v12, v13
	v_cvt_pk_f16_f32 v7, v10, v11
	v_cvt_pk_f16_f32 v12, v16, v17
	v_cvt_pk_f16_f32 v13, v14, v15
	global_store_dwordx2 v[38:39], v[18:19], off nt
	v_cvt_pk_fp8_f32 v127, v10, v11 op_sel:[0,0,1]
	v_cvt_pk_fp8_f32 v129, v14, v15 op_sel:[0,0,1]
	global_store_dword v116, v124, s[16:17] offset:2048 nt
	global_store_dwordx2 v[38:39], v[2:3], off offset:512 nt
	global_store_dword v116, v126, s[16:17] offset:2304 nt
	global_store_dwordx2 v[38:39], v[6:7], off offset:1024 nt
	global_store_dword v116, v127, s[16:17] offset:2560 nt
	global_store_dwordx2 v[38:39], v[12:13], off offset:1536 nt
	global_store_dword v116, v129, s[16:17] offset:2816 nt
	v_pk_mul_f32 v[90:91], v[90:91], v[134:135] op_sel_hi:[1,0]
	ds_read_b128 v[2:5], v1 offset:12288
	ds_read_b128 v[6:9], v1 offset:13312
	ds_read_b128 v[10:13], v1 offset:28672
	ds_read_b128 v[14:17], v1 offset:29696
	ds_read_b128 v[18:21], v1 offset:14336
	ds_read_b128 v[22:25], v1 offset:15360
	ds_read_b128 v[26:29], v1 offset:30720
	ds_read_b128 v[30:33], v1 offset:31744
	s_waitcnt lgkmcnt(5)
	v_pk_fma_f32 v[2:3], v[90:91], v[2:3], v[10:11]
	v_pk_mul_f32 v[94:95], v[94:95], v[134:135] op_sel_hi:[1,0]
	v_cvt_pk_fp8_f32 v128, v2, v3
	s_waitcnt lgkmcnt(4)
	v_pk_fma_f32 v[6:7], v[94:95], v[6:7], v[14:15]
	v_pk_mul_f32 v[92:93], v[92:93], v[134:135] op_sel_hi:[1,0]
	v_pk_mul_f32 v[96:97], v[96:97], v[134:135] op_sel_hi:[1,0]
	v_pk_mul_f32 v[98:99], v[98:99], v[134:135] op_sel_hi:[1,0]
	v_pk_mul_f32 v[102:103], v[102:103], v[134:135] op_sel_hi:[1,0]
	v_cvt_pk_fp8_f32 v130, v6, v7
	v_pk_fma_f32 v[4:5], v[92:93], v[4:5], v[12:13]
	v_pk_fma_f32 v[8:9], v[96:97], v[8:9], v[16:17]
	s_waitcnt lgkmcnt(1)
	v_pk_fma_f32 v[12:13], v[98:99], v[18:19], v[26:27]
	s_waitcnt lgkmcnt(0)
	v_pk_fma_f32 v[16:17], v[102:103], v[22:23], v[30:31]
	v_cvt_pk_fp8_f32 v131, v12, v13
	v_cvt_pk_fp8_f32 v132, v16, v17
	v_cvt_pk_fp8_f32 v128, v4, v5 op_sel:[0,0,1]
	v_pk_mul_f32 v[100:101], v[100:101], v[134:135] op_sel_hi:[1,0]
	v_pk_mul_f32 v[104:105], v[104:105], v[134:135] op_sel_hi:[1,0]
	v_cvt_pk_fp8_f32 v130, v8, v9 op_sel:[0,0,1]
	v_pk_fma_f32 v[10:11], v[100:101], v[20:21], v[28:29]
	v_pk_fma_f32 v[14:15], v[104:105], v[24:25], v[32:33]
	v_cvt_pk_f16_f32 v18, v2, v3
	v_cvt_pk_f16_f32 v19, v4, v5
	v_cvt_pk_f16_f32 v2, v6, v7
	v_cvt_pk_f16_f32 v3, v8, v9
	v_cvt_pk_f16_f32 v6, v12, v13
	v_cvt_pk_f16_f32 v7, v10, v11
	v_cvt_pk_f16_f32 v12, v16, v17
	v_cvt_pk_f16_f32 v13, v14, v15
	global_store_dwordx2 v[38:39], v[18:19], off offset:2048 nt
	v_cvt_pk_fp8_f32 v131, v10, v11 op_sel:[0,0,1]
	v_cvt_pk_fp8_f32 v132, v14, v15 op_sel:[0,0,1]
	global_store_dword v116, v128, s[16:17] offset:3072 nt
	global_store_dwordx2 v[38:39], v[2:3], off offset:2560 nt
	global_store_dword v116, v130, s[16:17] offset:3328 nt
	global_store_dwordx2 v[38:39], v[6:7], off offset:3072 nt
	global_store_dword v116, v131, s[16:17] offset:3584 nt
	global_store_dwordx2 v[38:39], v[12:13], off offset:3584 nt
	global_store_dword v116, v132, s[16:17] offset:3840 nt
	s_add_u32 s16, s16, s30
	s_addc_u32 s17, s17, s31
	s_add_u32 s6, s6, s14
	s_addc_u32 s7, s7, s15
	s_cmpk_lt_i32 s8, 0x4000
	s_cbranch_scc1 .LBB0_1395

.LBB0_1658:
	v_cmp_lt_i32_e32 vcc, v109, v108
	v_lshl_add_u64 v[0:1], s[8:9], 0, v[32:33]
	v_lshl_add_u64 v[8:9], v[0:1], 0, s[12:13]
	v_cndmask_b32_e32 v2, v107, v109, vcc
	v_cmp_lt_i32_e32 vcc, v110, v108
	global_load_dwordx2 v[42:43], v32, s[8:9]
	global_load_dwordx2 v[44:45], v32, s[8:9] offset:512
	global_load_dwordx2 v[46:47], v32, s[8:9] offset:1024
	global_load_dwordx2 v[48:49], v32, s[8:9] offset:1536
	global_load_dwordx2 v[50:51], v32, s[8:9] offset:2048
	global_load_dwordx2 v[52:53], v32, s[8:9] offset:2560
	v_cndmask_b32_e32 v3, v107, v110, vcc
	v_cmp_lt_i32_e32 vcc, v111, v108
	global_load_dwordx2 v[54:55], v32, s[8:9] offset:3072
	global_load_dwordx2 v[56:57], v32, s[8:9] offset:3584
	v_cndmask_b32_e32 v4, v107, v111, vcc
	v_cmp_lt_i32_e32 vcc, v112, v108
	global_load_dwordx2 v[58:59], v[8:9], off offset:512
	global_load_dwordx2 v[60:61], v[8:9], off offset:1024
	global_load_dwordx2 v[62:63], v[8:9], off offset:1536
	v_cndmask_b32_e32 v5, v107, v112, vcc
	v_cmp_lt_i32_e32 vcc, v113, v108
	v_lshlrev_b32_e32 v117, 2, v2
	v_lshlrev_b32_e32 v161, 2, v3
	v_cndmask_b32_e32 v6, v107, v113, vcc
	v_cmp_lt_i32_e32 vcc, v114, v108
	v_lshlrev_b32_e32 v164, 2, v4
	v_lshlrev_b32_e32 v165, 2, v5
	v_cndmask_b32_e32 v7, v107, v114, vcc
	v_add_co_u32_e32 v38, vcc, s3, v34
	v_lshlrev_b32_e32 v166, 2, v6
	s_nop 0
	v_addc_co_u32_e32 v39, vcc, 0, v35, vcc
	v_add_co_u32_e32 v36, vcc, s16, v34
	v_lshlrev_b32_e32 v167, 2, v7
	s_nop 0
	v_addc_co_u32_e32 v37, vcc, 0, v35, vcc
	v_add_co_u32_e32 v40, vcc, s17, v34
	s_add_i32 s2, s2, s4
	s_nop 0
	v_addc_co_u32_e32 v41, vcc, 0, v35, vcc
	v_add_co_u32_e32 v10, vcc, s3, v0
	s_add_u32 s8, s8, s10
	s_nop 0
	v_addc_co_u32_e32 v11, vcc, 0, v1, vcc
	global_load_dwordx2 v[64:65], v[8:9], off offset:2048
	global_load_dwordx2 v[66:67], v[8:9], off offset:2560
	global_load_dwordx2 v[68:69], v[8:9], off offset:3072
	global_load_dwordx2 v[70:71], v[10:11], off offset:512
	global_load_dwordx2 v[72:73], v[10:11], off offset:1024
	global_load_dwordx2 v[74:75], v[10:11], off offset:1536
	global_load_dwordx2 v[76:77], v[10:11], off offset:2048
	global_load_dwordx2 v[78:79], v[10:11], off offset:2560
	global_load_dwordx2 v[80:81], v[10:11], off offset:3072
	global_load_dwordx2 v[82:83], v[10:11], off offset:3584
	v_add_co_u32_e32 v0, vcc, s5, v0
	s_addc_u32 s9, s9, s11
	s_nop 0
	v_addc_co_u32_e32 v1, vcc, 0, v1, vcc
	global_load_dwordx2 v[84:85], v[10:11], off
	global_load_dwordx2 v[86:87], v[8:9], off offset:3584
	global_load_dwordx2 v[88:89], v[0:1], off offset:-4096
	global_load_dwordx2 v[90:91], v[0:1], off
	global_load_dwordx2 v[92:93], v[0:1], off offset:512
	global_load_dwordx2 v[94:95], v[0:1], off offset:1024
	global_load_dwordx2 v[96:97], v[0:1], off offset:1536
	global_load_dwordx2 v[98:99], v[0:1], off offset:2048
	global_load_dwordx2 v[100:101], v[0:1], off offset:2560
	global_load_dwordx2 v[102:103], v[0:1], off offset:3072
	global_load_dwordx2 v[104:105], v[0:1], off offset:3584
	ds_read_b128 v[8:11], v106
	ds_read_b128 v[0:3], v106 offset:1024
	ds_read_b128 v[24:27], v106 offset:16384
	ds_read_b128 v[16:19], v106 offset:17408
	ds_read_b128 v[12:15], v106 offset:2048
	ds_read_b128 v[4:7], v106 offset:3072
	ds_read_b128 v[28:31], v106 offset:18432
	ds_read_b128 v[20:23], v106 offset:19456
	s_cmpk_lt_i32 s2, 0x4000
	s_waitcnt vmcnt(31)
	v_lshlrev_b32_e32 v118, 16, v42
	v_and_b32_e32 v119, 0xffff0000, v42
	v_lshlrev_b32_e32 v120, 16, v43
	s_waitcnt vmcnt(28)
	v_lshlrev_b32_e32 v126, 16, v48
	v_and_b32_e32 v127, 0xffff0000, v48
	v_lshlrev_b32_e32 v128, 16, v49
	v_and_b32_e32 v129, 0xffff0000, v49
	v_and_b32_e32 v121, 0xffff0000, v43
	v_lshlrev_b32_e32 v42, 16, v44
	v_and_b32_e32 v43, 0xffff0000, v44
	v_lshlrev_b32_e32 v44, 16, v45
	v_and_b32_e32 v45, 0xffff0000, v45
	v_lshlrev_b32_e32 v122, 16, v46
	v_and_b32_e32 v123, 0xffff0000, v46
	v_lshlrev_b32_e32 v124, 16, v47
	v_and_b32_e32 v125, 0xffff0000, v47
	s_waitcnt vmcnt(27)
	v_lshlrev_b32_e32 v130, 16, v50
	v_and_b32_e32 v131, 0xffff0000, v50
	v_lshlrev_b32_e32 v132, 16, v51
	v_and_b32_e32 v133, 0xffff0000, v51
	s_waitcnt vmcnt(26)
	v_lshlrev_b32_e32 v134, 16, v52
	v_and_b32_e32 v135, 0xffff0000, v52
	v_lshlrev_b32_e32 v136, 16, v53
	v_and_b32_e32 v137, 0xffff0000, v53
	s_waitcnt vmcnt(25)
	v_lshlrev_b32_e32 v138, 16, v54
	v_and_b32_e32 v139, 0xffff0000, v54
	v_lshlrev_b32_e32 v140, 16, v55
	v_and_b32_e32 v141, 0xffff0000, v55
	s_waitcnt vmcnt(24)
	v_lshlrev_b32_e32 v142, 16, v56
	v_and_b32_e32 v143, 0xffff0000, v56
	v_lshlrev_b32_e32 v144, 16, v57
	v_and_b32_e32 v145, 0xffff0000, v57
	s_waitcnt vmcnt(21)
	v_fma_mix_f32 v50, v62, s14, v126 op_sel_hi:[1,0,0]
	v_fma_mix_f32 v51, v62, s14, v127 op_sel:[1,0,0] op_sel_hi:[1,0,0]
	v_fma_mix_f32 v52, v63, s14, v128 op_sel_hi:[1,0,0]
	v_fma_mix_f32 v53, v63, s14, v129 op_sel:[1,0,0] op_sel_hi:[1,0,0]
	v_fma_mix_f32 v42, v58, s14, v42 op_sel_hi:[1,0,0]
	v_fma_mix_f32 v43, v58, s14, v43 op_sel:[1,0,0] op_sel_hi:[1,0,0]
	v_fma_mix_f32 v44, v59, s14, v44 op_sel_hi:[1,0,0]
	v_fma_mix_f32 v45, v59, s14, v45 op_sel:[1,0,0] op_sel_hi:[1,0,0]
	v_fma_mix_f32 v46, v60, s14, v122 op_sel_hi:[1,0,0]
	v_fma_mix_f32 v47, v60, s14, v123 op_sel:[1,0,0] op_sel_hi:[1,0,0]
	v_fma_mix_f32 v48, v61, s14, v124 op_sel_hi:[1,0,0]
	v_fma_mix_f32 v49, v61, s14, v125 op_sel:[1,0,0] op_sel_hi:[1,0,0]
	s_waitcnt vmcnt(20)
	v_fma_mix_f32 v54, v64, s14, v130 op_sel_hi:[1,0,0]
	v_fma_mix_f32 v55, v64, s14, v131 op_sel:[1,0,0] op_sel_hi:[1,0,0]
	v_fma_mix_f32 v58, v65, s14, v132 op_sel_hi:[1,0,0]
	v_fma_mix_f32 v59, v65, s14, v133 op_sel:[1,0,0] op_sel_hi:[1,0,0]
	s_waitcnt vmcnt(19)
	v_fma_mix_f32 v56, v66, s14, v134 op_sel_hi:[1,0,0]
	v_fma_mix_f32 v57, v66, s14, v135 op_sel:[1,0,0] op_sel_hi:[1,0,0]
	v_fma_mix_f32 v62, v67, s14, v136 op_sel_hi:[1,0,0]
	v_fma_mix_f32 v63, v67, s14, v137 op_sel:[1,0,0] op_sel_hi:[1,0,0]
	s_waitcnt vmcnt(18)
	v_fma_mix_f32 v60, v68, s14, v138 op_sel_hi:[1,0,0]
	v_fma_mix_f32 v61, v68, s14, v139 op_sel:[1,0,0] op_sel_hi:[1,0,0]
	v_fma_mix_f32 v64, v69, s14, v140 op_sel_hi:[1,0,0]
	v_fma_mix_f32 v65, v69, s14, v141 op_sel:[1,0,0] op_sel_hi:[1,0,0]
	v_add_f32_e32 v126, v50, v51
	v_add_f32_e32 v127, v52, v53
	s_waitcnt vmcnt(9)
	v_fma_mix_f32 v66, v86, s14, v142 op_sel_hi:[1,0,0]
	v_fma_mix_f32 v67, v86, s14, v143 op_sel:[1,0,0] op_sel_hi:[1,0,0]
	v_fma_mix_f32 v68, v87, s14, v144 op_sel_hi:[1,0,0]
	v_fma_mix_f32 v69, v87, s14, v145 op_sel:[1,0,0] op_sel_hi:[1,0,0]
	v_lshlrev_b32_e32 v86, 16, v84
	v_and_b32_e32 v87, 0xffff0000, v84
	v_lshlrev_b32_e32 v134, 16, v85
	v_and_b32_e32 v135, 0xffff0000, v85
	v_lshlrev_b32_e32 v156, 16, v80
	v_and_b32_e32 v157, 0xffff0000, v80
	v_lshlrev_b32_e32 v158, 16, v81
	v_and_b32_e32 v159, 0xffff0000, v81
	s_waitcnt vmcnt(8)
	v_fma_mix_f32 v80, v88, s14, v118 op_sel_hi:[1,0,0]
	v_fma_mix_f32 v81, v88, s14, v119 op_sel:[1,0,0] op_sel_hi:[1,0,0]
	v_fma_mix_f32 v84, v89, s14, v120 op_sel_hi:[1,0,0]
	v_fma_mix_f32 v85, v89, s14, v121 op_sel:[1,0,0] op_sel_hi:[1,0,0]
	v_add_f32_e32 v120, v126, v127
	v_add_f32_e32 v126, v80, v81
	v_add_f32_e32 v127, v84, v85
	v_add_f32_e32 v122, v42, v43
	v_add_f32_e32 v123, v44, v45
	v_add_f32_e32 v126, v126, v127
	v_add_f32_e32 v124, v46, v47
	v_add_f32_e32 v125, v48, v49
	v_add_f32_e32 v118, v122, v123
	v_add_f32_e32 v126, 0, v126
	v_add_f32_e32 v119, v124, v125
	v_add_f32_e32 v118, v126, v118
	v_add_f32_e32 v128, v54, v55
	v_add_f32_e32 v129, v58, v59
	v_add_f32_e32 v118, v118, v119
	v_add_f32_e32 v130, v56, v57
	v_add_f32_e32 v131, v62, v63
	v_add_f32_e32 v121, v128, v129
	v_add_f32_e32 v118, v118, v120
	v_add_f32_e32 v132, v60, v61
	v_add_f32_e32 v133, v64, v65
	v_add_f32_e32 v122, v130, v131
	v_add_f32_e32 v118, v118, v121
	v_lshlrev_b32_e32 v136, 16, v70
	v_and_b32_e32 v137, 0xffff0000, v70
	v_lshlrev_b32_e32 v138, 16, v71
	v_and_b32_e32 v139, 0xffff0000, v71
	v_lshlrev_b32_e32 v144, 16, v74
	v_and_b32_e32 v145, 0xffff0000, v74
	v_lshlrev_b32_e32 v146, 16, v75
	v_and_b32_e32 v147, 0xffff0000, v75
	v_add_f32_e32 v123, v132, v133
	v_add_f32_e32 v124, v66, v67
	v_add_f32_e32 v125, v68, v69
	s_waitcnt vmcnt(7)
	v_fma_mix_f32 v70, v90, s14, v86 op_sel_hi:[1,0,0]
	v_fma_mix_f32 v71, v90, s14, v87 op_sel:[1,0,0] op_sel_hi:[1,0,0]
	v_fma_mix_f32 v74, v91, s14, v134 op_sel_hi:[1,0,0]
	v_fma_mix_f32 v75, v91, s14, v135 op_sel:[1,0,0] op_sel_hi:[1,0,0]
	v_add_f32_e32 v118, v118, v122
	v_lshlrev_b32_e32 v140, 16, v72
	v_and_b32_e32 v141, 0xffff0000, v72
	v_lshlrev_b32_e32 v142, 16, v73
	v_and_b32_e32 v143, 0xffff0000, v73
	v_lshlrev_b32_e32 v152, 16, v78
	v_and_b32_e32 v153, 0xffff0000, v78
	v_lshlrev_b32_e32 v154, 16, v79
	v_and_b32_e32 v155, 0xffff0000, v79
	s_waitcnt vmcnt(6)
	v_fma_mix_f32 v72, v92, s14, v136 op_sel_hi:[1,0,0]
	v_fma_mix_f32 v73, v92, s14, v137 op_sel:[1,0,0] op_sel_hi:[1,0,0]
	v_fma_mix_f32 v78, v93, s14, v138 op_sel_hi:[1,0,0]
	v_fma_mix_f32 v79, v93, s14, v139 op_sel:[1,0,0] op_sel_hi:[1,0,0]
	v_add_f32_e32 v124, v124, v125
	v_add_f32_e32 v125, v70, v71
	v_add_f32_e32 v128, v74, v75
	v_add_f32_e32 v118, v118, v123
	v_lshlrev_b32_e32 v148, 16, v76
	v_and_b32_e32 v149, 0xffff0000, v76
	v_lshlrev_b32_e32 v150, 16, v77
	v_and_b32_e32 v151, 0xffff0000, v77
	s_waitcnt vmcnt(5)
	v_fma_mix_f32 v76, v94, s14, v140 op_sel_hi:[1,0,0]
	v_fma_mix_f32 v77, v94, s14, v141 op_sel:[1,0,0] op_sel_hi:[1,0,0]
	v_fma_mix_f32 v86, v95, s14, v142 op_sel_hi:[1,0,0]
	v_fma_mix_f32 v87, v95, s14, v143 op_sel:[1,0,0] op_sel_hi:[1,0,0]
	v_add_f32_e32 v129, v72, v73
	v_add_f32_e32 v130, v78, v79
	v_add_f32_e32 v125, v125, v128
	v_add_f32_e32 v118, v118, v124
	v_lshlrev_b32_e32 v160, 16, v82
	v_and_b32_e32 v162, 0xffff0000, v82
	v_lshlrev_b32_e32 v163, 16, v83
	v_and_b32_e32 v168, 0xffff0000, v83
	s_waitcnt vmcnt(4)
	v_fma_mix_f32 v82, v96, s14, v144 op_sel_hi:[1,0,0]
	v_fma_mix_f32 v83, v96, s14, v145 op_sel:[1,0,0] op_sel_hi:[1,0,0]
	v_fma_mix_f32 v90, v97, s14, v146 op_sel_hi:[1,0,0]
	v_fma_mix_f32 v91, v97, s14, v147 op_sel:[1,0,0] op_sel_hi:[1,0,0]
	v_add_f32_e32 v131, v76, v77
	v_add_f32_e32 v132, v86, v87
	v_add_f32_e32 v127, v129, v130
	v_add_f32_e32 v118, v118, v125
	s_waitcnt vmcnt(3)
	v_fma_mix_f32 v88, v98, s14, v148 op_sel_hi:[1,0,0]
	v_fma_mix_f32 v89, v98, s14, v149 op_sel:[1,0,0] op_sel_hi:[1,0,0]
	v_fma_mix_f32 v94, v99, s14, v150 op_sel_hi:[1,0,0]
	v_fma_mix_f32 v95, v99, s14, v151 op_sel:[1,0,0] op_sel_hi:[1,0,0]
	v_add_f32_e32 v133, v82, v83
	v_add_f32_e32 v134, v90, v91
	v_add_f32_e32 v128, v131, v132
	v_add_f32_e32 v118, v118, v127
	s_waitcnt vmcnt(2)
	v_fma_mix_f32 v92, v100, s14, v152 op_sel_hi:[1,0,0]
	v_fma_mix_f32 v93, v100, s14, v153 op_sel:[1,0,0] op_sel_hi:[1,0,0]
	v_fma_mix_f32 v98, v101, s14, v154 op_sel_hi:[1,0,0]
	v_fma_mix_f32 v99, v101, s14, v155 op_sel:[1,0,0] op_sel_hi:[1,0,0]
	v_add_f32_e32 v135, v88, v89
	v_add_f32_e32 v136, v94, v95
	v_add_f32_e32 v129, v133, v134
	v_add_f32_e32 v118, v118, v128
	s_waitcnt vmcnt(1)
	v_fma_mix_f32 v96, v102, s14, v156 op_sel_hi:[1,0,0]
	v_fma_mix_f32 v97, v102, s14, v157 op_sel:[1,0,0] op_sel_hi:[1,0,0]
	v_fma_mix_f32 v102, v103, s14, v158 op_sel_hi:[1,0,0]
	v_fma_mix_f32 v103, v103, s14, v159 op_sel:[1,0,0] op_sel_hi:[1,0,0]
	v_add_f32_e32 v137, v92, v93
	v_add_f32_e32 v138, v98, v99
	v_add_f32_e32 v130, v135, v136
	v_add_f32_e32 v118, v118, v129
	s_waitcnt vmcnt(0)
	v_fma_mix_f32 v100, v104, s14, v160 op_sel_hi:[1,0,0]
	v_fma_mix_f32 v101, v104, s14, v162 op_sel:[1,0,0] op_sel_hi:[1,0,0]
	v_fma_mix_f32 v104, v105, s14, v163 op_sel_hi:[1,0,0]
	v_fma_mix_f32 v105, v105, s14, v168 op_sel:[1,0,0] op_sel_hi:[1,0,0]
	v_add_f32_e32 v139, v96, v97
	v_add_f32_e32 v140, v102, v103
	v_add_f32_e32 v131, v137, v138
	v_add_f32_e32 v118, v118, v130
	v_add_f32_e32 v141, v100, v101
	v_add_f32_e32 v142, v104, v105
	v_add_f32_e32 v132, v139, v140
	v_add_f32_e32 v118, v118, v131
	v_add_f32_e32 v133, v141, v142
	v_add_f32_e32 v118, v118, v132
	v_add_f32_e32 v118, v118, v133
	ds_bpermute_b32 v119, v117, v118
	s_waitcnt lgkmcnt(0)
	v_add_f32_e32 v118, v118, v119
	ds_bpermute_b32 v119, v161, v118
	s_waitcnt lgkmcnt(0)
	v_add_f32_e32 v118, v118, v119
	ds_bpermute_b32 v119, v164, v118
	s_waitcnt lgkmcnt(0)
	v_add_f32_e32 v118, v118, v119
	ds_bpermute_b32 v119, v165, v118
	s_waitcnt lgkmcnt(0)
	v_add_f32_e32 v118, v118, v119
	ds_bpermute_b32 v119, v166, v118
	s_waitcnt lgkmcnt(0)
	v_add_f32_e32 v118, v118, v119
	ds_bpermute_b32 v119, v167, v118
	s_waitcnt lgkmcnt(0)
	v_add_f32_e32 v118, v118, v119
	v_fmac_f32_e32 v81, 0xb9800000, v118
	v_fmac_f32_e32 v80, 0xb9800000, v118
	v_fmac_f32_e32 v85, 0xb9800000, v118
	v_fmac_f32_e32 v84, 0xb9800000, v118
	v_fmac_f32_e32 v43, 0xb9800000, v118
	v_fmac_f32_e32 v42, 0xb9800000, v118
	v_fmac_f32_e32 v45, 0xb9800000, v118
	v_fmac_f32_e32 v44, 0xb9800000, v118
	v_fmac_f32_e32 v47, 0xb9800000, v118
	v_fmac_f32_e32 v46, 0xb9800000, v118
	v_fmac_f32_e32 v49, 0xb9800000, v118
	v_fmac_f32_e32 v48, 0xb9800000, v118
	v_fmac_f32_e32 v53, 0xb9800000, v118
	v_fmac_f32_e32 v52, 0xb9800000, v118
	v_fmac_f32_e32 v51, 0xb9800000, v118
	v_fmac_f32_e32 v50, 0xb9800000, v118
	v_fmac_f32_e32 v55, 0xb9800000, v118
	v_fmac_f32_e32 v54, 0xb9800000, v118
	v_fmac_f32_e32 v59, 0xb9800000, v118
	v_fmac_f32_e32 v58, 0xb9800000, v118
	v_fmac_f32_e32 v57, 0xb9800000, v118
	v_fmac_f32_e32 v56, 0xb9800000, v118
	v_fmac_f32_e32 v63, 0xb9800000, v118
	v_fmac_f32_e32 v62, 0xb9800000, v118
	v_fmac_f32_e32 v65, 0xb9800000, v118
	v_fmac_f32_e32 v64, 0xb9800000, v118
	v_fmac_f32_e32 v61, 0xb9800000, v118
	v_fmac_f32_e32 v60, 0xb9800000, v118
	v_fmac_f32_e32 v67, 0xb9800000, v118
	v_fmac_f32_e32 v66, 0xb9800000, v118
	v_fmac_f32_e32 v69, 0xb9800000, v118
	v_fmac_f32_e32 v68, 0xb9800000, v118
	v_fmac_f32_e32 v71, 0xb9800000, v118
	v_fmac_f32_e32 v70, 0xb9800000, v118
	v_fmac_f32_e32 v75, 0xb9800000, v118
	v_fmac_f32_e32 v74, 0xb9800000, v118
	v_fmac_f32_e32 v79, 0xb9800000, v118
	v_fmac_f32_e32 v78, 0xb9800000, v118
	v_fmac_f32_e32 v73, 0xb9800000, v118
	v_fmac_f32_e32 v72, 0xb9800000, v118
	v_fmac_f32_e32 v77, 0xb9800000, v118
	v_fmac_f32_e32 v76, 0xb9800000, v118
	v_fmac_f32_e32 v87, 0xb9800000, v118
	v_fmac_f32_e32 v86, 0xb9800000, v118
	v_fmac_f32_e32 v83, 0xb9800000, v118
	v_fmac_f32_e32 v82, 0xb9800000, v118
	v_fmac_f32_e32 v91, 0xb9800000, v118
	v_fmac_f32_e32 v90, 0xb9800000, v118
	v_fmac_f32_e32 v95, 0xb9800000, v118
	v_fmac_f32_e32 v94, 0xb9800000, v118
	v_fmac_f32_e32 v89, 0xb9800000, v118
	v_fmac_f32_e32 v88, 0xb9800000, v118
	v_fmac_f32_e32 v93, 0xb9800000, v118
	v_fmac_f32_e32 v92, 0xb9800000, v118
	v_fmac_f32_e32 v99, 0xb9800000, v118
	v_fmac_f32_e32 v98, 0xb9800000, v118
	v_fmac_f32_e32 v97, 0xb9800000, v118
	v_fmac_f32_e32 v96, 0xb9800000, v118
	v_fmac_f32_e32 v103, 0xb9800000, v118
	v_fmac_f32_e32 v102, 0xb9800000, v118
	v_fmac_f32_e32 v105, 0xb9800000, v118
	v_fmac_f32_e32 v104, 0xb9800000, v118
	v_fmac_f32_e32 v101, 0xb9800000, v118
	v_fmac_f32_e32 v100, 0xb9800000, v118
	v_pk_mul_f32 v[118:119], v[84:85], v[84:85]
	v_pk_mul_f32 v[120:121], v[80:81], v[80:81]
	v_pk_mul_f32 v[122:123], v[44:45], v[44:45]
	v_pk_mul_f32 v[124:125], v[42:43], v[42:43]
	v_pk_mov_b32 v[162:163], v[120:121], v[118:119] op_sel:[1,0]
	v_mov_b32_e32 v121, v119
	v_pk_mov_b32 v[118:119], v[124:125], v[122:123] op_sel:[1,0]
	v_mov_b32_e32 v125, v123
	v_mul_f32_e32 v126, v46, v46
	v_mul_f32_e32 v128, v48, v48
	v_pk_add_f32 v[120:121], v[162:163], v[120:121]
	v_pk_add_f32 v[118:119], v[118:119], v[124:125]
	v_pk_fma_f32 v[122:123], v[46:47], v[46:47], v[126:127] op_sel_hi:[1,1,0]
	v_pk_fma_f32 v[126:127], v[48:49], v[48:49], v[128:129] op_sel_hi:[1,1,0]
	v_pk_add_f32 v[120:121], v[120:121], v[120:121] op_sel_hi:[0,1]
	v_pk_add_f32 v[118:119], v[118:119], v[118:119] op_sel_hi:[0,1]
	v_pk_mul_f32 v[130:131], v[58:59], v[58:59]
	v_pk_mul_f32 v[132:133], v[54:55], v[54:55]
	v_mul_f32_e32 v122, v50, v50
	v_mul_f32_e32 v126, v51, v51
	v_mul_f32_e32 v120, v52, v52
	v_mul_f32_e32 v118, v53, v53
	v_pk_mov_b32 v[128:129], v[132:133], v[130:131] op_sel:[1,0]
	v_mov_b32_e32 v133, v131
	v_pk_add_f32 v[122:123], v[122:123], v[126:127]
	v_pk_add_f32 v[118:119], v[120:121], v[118:119]
	v_mul_f32_e32 v134, v56, v56
	v_mul_f32_e32 v136, v62, v62
	v_pk_add_f32 v[124:125], v[128:129], v[132:133]
	v_pk_add_f32 v[118:119], v[122:123], v[118:119]
	v_pk_fma_f32 v[130:131], v[56:57], v[56:57], v[134:135] op_sel_hi:[1,1,0]
	v_pk_fma_f32 v[134:135], v[62:63], v[62:63], v[136:137] op_sel_hi:[1,1,0]
	v_pk_add_f32 v[124:125], v[124:125], v[124:125] op_sel_hi:[0,1]
	v_pk_add_f32 v[118:119], v[118:119], v[118:119] op_sel_hi:[0,1]
	v_pk_mul_f32 v[138:139], v[68:69], v[68:69]
	v_pk_mul_f32 v[140:141], v[66:67], v[66:67]
	v_mul_f32_e32 v130, v60, v60
	v_mul_f32_e32 v134, v61, v61
	v_mul_f32_e32 v124, v64, v64
	v_mul_f32_e32 v118, v65, v65
	v_pk_mov_b32 v[136:137], v[140:141], v[138:139] op_sel:[1,0]
	v_mov_b32_e32 v141, v139
	v_pk_add_f32 v[126:127], v[130:131], v[134:135]
	v_pk_add_f32 v[118:119], v[124:125], v[118:119]
	v_mul_f32_e32 v142, v70, v70
	v_mul_f32_e32 v144, v74, v74
	v_pk_add_f32 v[128:129], v[136:137], v[140:141]
	v_pk_add_f32 v[118:119], v[126:127], v[118:119]
	v_pk_fma_f32 v[138:139], v[70:71], v[70:71], v[142:143] op_sel_hi:[1,1,0]
	v_pk_fma_f32 v[142:143], v[74:75], v[74:75], v[144:145] op_sel_hi:[1,1,0]
	v_pk_add_f32 v[128:129], v[128:129], v[128:129] op_sel_hi:[0,1]
	v_pk_add_f32 v[118:119], v[118:119], v[118:119] op_sel_hi:[0,1]
	v_pk_mul_f32 v[146:147], v[86:87], v[86:87]
	v_pk_mul_f32 v[148:149], v[76:77], v[76:77]
	v_mul_f32_e32 v138, v72, v72
	v_mul_f32_e32 v142, v73, v73
	v_mul_f32_e32 v128, v78, v78
	v_mul_f32_e32 v118, v79, v79
	v_pk_mov_b32 v[144:145], v[148:149], v[146:147] op_sel:[1,0]
	v_mov_b32_e32 v149, v147
	v_pk_add_f32 v[130:131], v[138:139], v[142:143]
	v_pk_add_f32 v[118:119], v[128:129], v[118:119]
	v_mul_f32_e32 v150, v82, v82
	v_mul_f32_e32 v152, v90, v90
	v_pk_add_f32 v[132:133], v[144:145], v[148:149]
	v_pk_add_f32 v[118:119], v[130:131], v[118:119]
	v_pk_fma_f32 v[146:147], v[82:83], v[82:83], v[150:151] op_sel_hi:[1,1,0]
	v_pk_fma_f32 v[150:151], v[90:91], v[90:91], v[152:153] op_sel_hi:[1,1,0]
	v_pk_add_f32 v[132:133], v[132:133], v[132:133] op_sel_hi:[0,1]
	v_pk_add_f32 v[118:119], v[118:119], v[118:119] op_sel_hi:[0,1]
	v_pk_mul_f32 v[154:155], v[98:99], v[98:99]
	v_pk_mul_f32 v[156:157], v[92:93], v[92:93]
	v_mul_f32_e32 v146, v88, v88
	v_mul_f32_e32 v150, v89, v89
	v_mul_f32_e32 v132, v94, v94
	v_mul_f32_e32 v118, v95, v95
	v_pk_mov_b32 v[152:153], v[156:157], v[154:155] op_sel:[1,0]
	v_mov_b32_e32 v157, v155
	v_pk_add_f32 v[134:135], v[146:147], v[150:151]
	v_pk_add_f32 v[118:119], v[132:133], v[118:119]
	v_mul_f32_e32 v158, v96, v96
	v_mul_f32_e32 v160, v102, v102
	v_pk_add_f32 v[136:137], v[152:153], v[156:157]
	v_pk_add_f32 v[118:119], v[134:135], v[118:119]
	v_pk_fma_f32 v[154:155], v[96:97], v[96:97], v[158:159] op_sel_hi:[1,1,0]
	v_pk_fma_f32 v[158:159], v[102:103], v[102:103], v[160:161] op_sel_hi:[1,1,0]
	v_pk_add_f32 v[136:137], v[136:137], v[136:137] op_sel_hi:[0,1]
	v_pk_add_f32 v[118:119], v[118:119], v[118:119] op_sel_hi:[0,1]
	v_mul_f32_e32 v154, v100, v100
	v_mul_f32_e32 v158, v101, v101
	v_mul_f32_e32 v136, v104, v104
	v_mul_f32_e32 v118, v105, v105
	v_pk_add_f32 v[138:139], v[154:155], v[158:159]
	v_pk_add_f32 v[118:119], v[136:137], v[118:119]
	s_nop 0
	v_pk_add_f32 v[118:119], v[138:139], v[118:119]
	s_nop 0
	v_add_f32_e32 v118, v118, v119
	ds_bpermute_b32 v117, v117, v118
	s_waitcnt lgkmcnt(0)
	v_add_f32_e32 v117, v118, v117
	ds_bpermute_b32 v118, v161, v117
	s_waitcnt lgkmcnt(0)
	v_add_f32_e32 v117, v117, v118
	ds_bpermute_b32 v118, v164, v117
	s_waitcnt lgkmcnt(0)
	v_add_f32_e32 v117, v117, v118
	ds_bpermute_b32 v118, v165, v117
	s_waitcnt lgkmcnt(0)
	v_add_f32_e32 v117, v117, v118
	ds_bpermute_b32 v118, v166, v117
	s_waitcnt lgkmcnt(0)
	v_add_f32_e32 v117, v117, v118
	ds_bpermute_b32 v118, v167, v117
	s_waitcnt lgkmcnt(0)
	v_add_f32_e32 v117, v117, v118
	v_fmamk_f32 v117, v117, 0x39800000, v115
	v_mul_f32_e32 v118, 0x4f800000, v117
	v_cmp_gt_f32_e32 vcc, s15, v117
	s_nop 1
	v_cndmask_b32_e32 v117, v117, v118, vcc
	v_sqrt_f32_e32 v118, v117
	s_nop 0
	v_add_u32_e32 v119, -1, v118
	v_add_u32_e32 v120, 1, v118
	v_fma_f32 v121, -v119, v118, v117
	v_fma_f32 v122, -v120, v118, v117
	v_cmp_ge_f32_e64 s[0:1], 0, v121
	s_nop 1
	v_cndmask_b32_e64 v118, v118, v119, s[0:1]
	v_cmp_lt_f32_e64 s[0:1], 0, v122
	s_nop 1
	v_cndmask_b32_e64 v118, v118, v120, s[0:1]
	v_mul_f32_e32 v119, 0x37800000, v118
	v_cndmask_b32_e32 v118, v118, v119, vcc
	v_cmp_class_f32_e32 vcc, v117, v116
	s_nop 1
	v_cndmask_b32_e32 v117, v118, v117, vcc
	v_div_scale_f32 v118, s[0:1], v117, v117, 1.0
	v_rcp_f32_e32 v120, v118
	v_div_scale_f32 v119, vcc, 1.0, v117, 1.0
	v_fma_f32 v121, -v118, v120, 1.0
	v_fmac_f32_e32 v120, v121, v120
	v_mul_f32_e32 v121, v119, v120
	v_fma_f32 v122, -v118, v121, v119
	v_fmac_f32_e32 v121, v122, v120
	v_fma_f32 v118, -v118, v121, v119
	v_div_fmas_f32 v118, v118, v120, v121
	v_div_fixup_f32 v118, v118, v117, 1.0
	v_pk_mul_f32 v[80:81], v[80:81], v[118:119] op_sel_hi:[1,0]
	v_pk_mul_f32 v[84:85], v[84:85], v[118:119] op_sel_hi:[1,0]
	v_pk_mul_f32 v[42:43], v[42:43], v[118:119] op_sel_hi:[1,0]
	v_pk_mul_f32 v[44:45], v[44:45], v[118:119] op_sel_hi:[1,0]
	v_pk_mul_f32 v[46:47], v[46:47], v[118:119] op_sel_hi:[1,0]
	v_pk_mul_f32 v[48:49], v[48:49], v[118:119] op_sel_hi:[1,0]
	v_pk_mul_f32 v[50:51], v[50:51], v[118:119] op_sel_hi:[1,0]
	v_pk_mul_f32 v[52:53], v[52:53], v[118:119] op_sel_hi:[1,0]
	v_pk_fma_f32 v[10:11], v[10:11], v[84:85], v[26:27]
	v_pk_fma_f32 v[8:9], v[8:9], v[80:81], v[24:25]
	v_pk_fma_f32 v[2:3], v[2:3], v[44:45], v[18:19]
	v_pk_fma_f32 v[0:1], v[0:1], v[42:43], v[16:17]
	v_pk_fma_f32 v[14:15], v[14:15], v[48:49], v[30:31]
	v_pk_fma_f32 v[12:13], v[12:13], v[46:47], v[28:29]
	v_pk_fma_f32 v[6:7], v[6:7], v[52:53], v[22:23]
	v_pk_fma_f32 v[4:5], v[4:5], v[50:51], v[20:21]
	global_store_dwordx4 v[34:35], v[8:11], off nt
	global_store_dwordx4 v[34:35], v[0:3], off offset:1024 nt
	global_store_dwordx4 v[34:35], v[12:15], off offset:2048 nt
	global_store_dwordx4 v[34:35], v[4:7], off offset:3072 nt
	ds_read_b128 v[0:3], v106 offset:4096
	ds_read_b128 v[4:7], v106 offset:5120
	ds_read_b128 v[8:11], v106 offset:20480
	ds_read_b128 v[12:15], v106 offset:21504
	ds_read_b128 v[16:19], v106 offset:6144
	ds_read_b128 v[20:23], v106 offset:7168
	ds_read_b128 v[24:27], v106 offset:22528
	ds_read_b128 v[28:31], v106 offset:23552
	v_pk_mul_f32 v[58:59], v[58:59], v[118:119] op_sel_hi:[1,0]
	v_pk_mul_f32 v[54:55], v[54:55], v[118:119] op_sel_hi:[1,0]
	v_pk_mul_f32 v[62:63], v[62:63], v[118:119] op_sel_hi:[1,0]
	v_pk_mul_f32 v[56:57], v[56:57], v[118:119] op_sel_hi:[1,0]
	v_pk_mul_f32 v[64:65], v[64:65], v[118:119] op_sel_hi:[1,0]
	v_pk_mul_f32 v[60:61], v[60:61], v[118:119] op_sel_hi:[1,0]
	v_pk_mul_f32 v[68:69], v[68:69], v[118:119] op_sel_hi:[1,0]
	v_pk_mul_f32 v[66:67], v[66:67], v[118:119] op_sel_hi:[1,0]
	s_waitcnt lgkmcnt(5)
	v_pk_fma_f32 v[0:1], v[0:1], v[54:55], v[8:9]
	v_pk_fma_f32 v[2:3], v[2:3], v[58:59], v[10:11]
	s_waitcnt lgkmcnt(4)
	v_pk_fma_f32 v[4:5], v[4:5], v[56:57], v[12:13]
	v_pk_fma_f32 v[6:7], v[6:7], v[62:63], v[14:15]
	s_waitcnt lgkmcnt(1)
	v_pk_fma_f32 v[8:9], v[16:17], v[60:61], v[24:25]
	v_pk_fma_f32 v[10:11], v[18:19], v[64:65], v[26:27]
	s_waitcnt lgkmcnt(0)
	v_pk_fma_f32 v[12:13], v[20:21], v[66:67], v[28:29]
	v_pk_fma_f32 v[14:15], v[22:23], v[68:69], v[30:31]
	global_store_dwordx4 v[36:37], v[0:3], off offset:-4096 nt
	global_store_dwordx4 v[38:39], v[4:7], off offset:1024 nt
	global_store_dwordx4 v[38:39], v[8:11], off offset:2048 nt
	global_store_dwordx4 v[38:39], v[12:15], off offset:3072 nt
	ds_read_b128 v[0:3], v106 offset:8192
	ds_read_b128 v[4:7], v106 offset:9216
	ds_read_b128 v[8:11], v106 offset:24576
	ds_read_b128 v[12:15], v106 offset:25600
	ds_read_b128 v[16:19], v106 offset:10240
	ds_read_b128 v[20:23], v106 offset:11264
	ds_read_b128 v[24:27], v106 offset:26624
	ds_read_b128 v[28:31], v106 offset:27648
	v_pk_mul_f32 v[74:75], v[74:75], v[118:119] op_sel_hi:[1,0]
	v_pk_mul_f32 v[70:71], v[70:71], v[118:119] op_sel_hi:[1,0]
	v_pk_mul_f32 v[78:79], v[78:79], v[118:119] op_sel_hi:[1,0]
	v_pk_mul_f32 v[72:73], v[72:73], v[118:119] op_sel_hi:[1,0]
	v_pk_mul_f32 v[86:87], v[86:87], v[118:119] op_sel_hi:[1,0]
	v_pk_mul_f32 v[76:77], v[76:77], v[118:119] op_sel_hi:[1,0]
	v_pk_mul_f32 v[90:91], v[90:91], v[118:119] op_sel_hi:[1,0]
	v_pk_mul_f32 v[82:83], v[82:83], v[118:119] op_sel_hi:[1,0]
	s_waitcnt lgkmcnt(5)
	v_pk_fma_f32 v[0:1], v[0:1], v[70:71], v[8:9]
	v_pk_fma_f32 v[2:3], v[2:3], v[74:75], v[10:11]
	s_waitcnt lgkmcnt(4)
	v_pk_fma_f32 v[4:5], v[4:5], v[72:73], v[12:13]
	v_pk_fma_f32 v[6:7], v[6:7], v[78:79], v[14:15]
	s_waitcnt lgkmcnt(1)
	v_pk_fma_f32 v[8:9], v[16:17], v[76:77], v[24:25]
	v_pk_fma_f32 v[10:11], v[18:19], v[86:87], v[26:27]
	s_waitcnt lgkmcnt(0)
	v_pk_fma_f32 v[12:13], v[82:83], v[20:21], v[28:29]
	v_pk_fma_f32 v[14:15], v[90:91], v[22:23], v[30:31]
	global_store_dwordx4 v[36:37], v[0:3], off nt
	global_store_dwordx4 v[36:37], v[4:7], off offset:1024 nt
	global_store_dwordx4 v[36:37], v[8:11], off offset:2048 nt
	global_store_dwordx4 v[36:37], v[12:15], off offset:3072 nt
	ds_read_b128 v[0:3], v106 offset:12288
	ds_read_b128 v[4:7], v106 offset:13312
	ds_read_b128 v[8:11], v106 offset:28672
	ds_read_b128 v[12:15], v106 offset:29696
	ds_read_b128 v[16:19], v106 offset:14336
	ds_read_b128 v[20:23], v106 offset:15360
	ds_read_b128 v[24:27], v106 offset:30720
	ds_read_b128 v[28:31], v106 offset:31744
	v_pk_mul_f32 v[94:95], v[94:95], v[118:119] op_sel_hi:[1,0]
	v_pk_mul_f32 v[88:89], v[88:89], v[118:119] op_sel_hi:[1,0]
	v_pk_mul_f32 v[98:99], v[98:99], v[118:119] op_sel_hi:[1,0]
	v_pk_mul_f32 v[92:93], v[92:93], v[118:119] op_sel_hi:[1,0]
	v_pk_mul_f32 v[102:103], v[102:103], v[118:119] op_sel_hi:[1,0]
	v_pk_mul_f32 v[96:97], v[96:97], v[118:119] op_sel_hi:[1,0]
	v_pk_mul_f32 v[104:105], v[104:105], v[118:119] op_sel_hi:[1,0]
	v_pk_mul_f32 v[100:101], v[100:101], v[118:119] op_sel_hi:[1,0]
	v_lshl_add_u64 v[34:35], v[34:35], 0, s[6:7]
	s_waitcnt lgkmcnt(5)
	v_pk_fma_f32 v[0:1], v[88:89], v[0:1], v[8:9]
	v_pk_fma_f32 v[2:3], v[94:95], v[2:3], v[10:11]
	s_waitcnt lgkmcnt(4)
	v_pk_fma_f32 v[4:5], v[92:93], v[4:5], v[12:13]
	v_pk_fma_f32 v[6:7], v[98:99], v[6:7], v[14:15]
	s_waitcnt lgkmcnt(1)
	v_pk_fma_f32 v[8:9], v[96:97], v[16:17], v[24:25]
	v_pk_fma_f32 v[10:11], v[102:103], v[18:19], v[26:27]
	s_waitcnt lgkmcnt(0)
	v_pk_fma_f32 v[12:13], v[100:101], v[20:21], v[28:29]
	v_pk_fma_f32 v[14:15], v[104:105], v[22:23], v[30:31]
	global_store_dwordx4 v[40:41], v[0:3], off nt
	global_store_dwordx4 v[40:41], v[4:7], off offset:1024 nt
	global_store_dwordx4 v[40:41], v[8:11], off offset:2048 nt
	global_store_dwordx4 v[40:41], v[12:15], off offset:3072 nt
	s_cbranch_scc1 .LBB0_1658
